# fold x16 output scale into per-row reciprocal in mem/SWA/DSA epilogues (bit-exact; 45 VALU deleted, 83 turned into s_nop 0 spacers after trans ops)
# baseline (speedup 1.0000x reference)
; template <int DQK, int W1, int DV, int VW, int MODE> ...
;     ...
;         f32x16 e0 = s[0], e1 = s[1];
;         if (MODE != 0) { const float nm = -m; e0 = e0 + nm; e1 = e1 + nm; }
; #pragma unroll
;         for (int i = 0; i < 16; ++i) { e0[i] = __builtin_amdgcn_exp2f(e0[i]); e1[i] = __builtin_amdgcn_exp2f(e1[i]); }
;         s[0] = e0; s[1] = e1;
;         const f32x16 sm = e0 + e1;
;         typedef __attribute__((ext_vector_type(8))) float f32x8;
;         const f32x8 h8 = sm.lo + sm.hi;
;         const f32x4 h4 = h8.lo + h8.hi;
;         const f32x2 h2 = h4.lo + h4.hi;
;         l += h2[0] + h2[1];
;       }
;       bf16x8 pb[2][2];
; #pragma unroll
;       for (int n = 0; n < 2; ++n)
; #pragma unroll
;         for (int s2 = 0; s2 < 2; ++s2) {
;           u32x4 pw = {pk2(s[n][8 * s2 + 0], s[n][8 * s2 + 1]), pk2(s[n][8 * s2 + 2], s[n][8 * s2 + 3]),
;                       pk2(s[n][8 * s2 + 4], s[n][8 * s2 + 5]), pk2(s[n][8 * s2 + 6], s[n][8 * s2 + 7])};
;           pb[n][s2] = __builtin_bit_cast(bf16x8, pw);
;         }
;       pv_block<0>(o[0], bufa + vlane, pb);
;       if constexpr (NCB > 1) pv_block<1>(o[1], bufa + vlane, pb);
;       if constexpr (NCB > 2) pv_block<2>(o[2], bufa + vlane, pb);
;       if constexpr (NCB > 3) pv_block<3>(o[3], bufa + vlane, pb);
;     }
;     asm volatile("s_waitcnt vmcnt(0)" ::: "memory");
;     __syncthreads();
.LBB0_1291:
	v_pk_add_f32 v[96:97], v[108:109], v[94:95] op_sel_hi:[1,0]
	v_pk_add_f32 v[98:99], v[106:107], v[94:95] op_sel_hi:[1,0]
	v_pk_add_f32 v[100:101], v[104:105], v[94:95] op_sel_hi:[1,0]
	v_pk_add_f32 v[102:103], v[102:103], v[94:95] op_sel_hi:[1,0]
	v_pk_add_f32 v[72:73], v[72:73], v[94:95] op_sel_hi:[1,0]
	v_pk_add_f32 v[70:71], v[70:71], v[94:95] op_sel_hi:[1,0]
	v_pk_add_f32 v[68:69], v[68:69], v[94:95] op_sel_hi:[1,0]
	v_mov_b32_e32 v95, v94
	v_mov_b64_e32 v[74:75], s[82:83]
	v_pk_add_f32 v[66:67], v[66:67], v[94:95]
	v_pk_add_f32 v[92:93], v[92:93], v[94:95] op_sel_hi:[1,0]
	v_pk_add_f32 v[90:91], v[90:91], v[94:95] op_sel_hi:[1,0]
	v_pk_add_f32 v[86:87], v[86:87], v[94:95] op_sel_hi:[1,0]
	v_pk_add_f32 v[84:85], v[84:85], v[94:95] op_sel_hi:[1,0]
	v_pk_add_f32 v[82:83], v[82:83], v[94:95] op_sel_hi:[1,0]
	v_pk_add_f32 v[80:81], v[80:81], v[94:95] op_sel_hi:[1,0]
	v_pk_add_f32 v[78:79], v[78:79], v[94:95] op_sel_hi:[1,0]
	v_pk_add_f32 v[76:77], v[76:77], v[94:95]
	v_mad_u64_u32 v[74:75], s[0:1], v166, s34, v[74:75]
	v_exp_f32_e32 v66, v66
	v_exp_f32_e32 v76, v76
	v_exp_f32_e32 v67, v67
	v_exp_f32_e32 v77, v77
	v_exp_f32_e32 v68, v68
	v_exp_f32_e32 v78, v78
	v_exp_f32_e32 v69, v69
	v_exp_f32_e32 v79, v79
	v_exp_f32_e32 v70, v70
	v_exp_f32_e32 v80, v80
	v_exp_f32_e32 v71, v71
	v_exp_f32_e32 v81, v81
	v_exp_f32_e32 v72, v72
	v_exp_f32_e32 v82, v82
	v_exp_f32_e32 v73, v73
	v_exp_f32_e32 v83, v83
	v_exp_f32_e32 v94, v102
	v_exp_f32_e32 v84, v84
	v_exp_f32_e32 v95, v103
	v_exp_f32_e32 v85, v85
	v_exp_f32_e32 v100, v100
	v_exp_f32_e32 v86, v86
	v_exp_f32_e32 v101, v101
	v_exp_f32_e32 v87, v87
	v_exp_f32_e32 v98, v98
	v_exp_f32_e32 v90, v90
	v_exp_f32_e32 v99, v99
	v_exp_f32_e32 v91, v91
	v_exp_f32_e32 v96, v96
	v_exp_f32_e32 v92, v92
	v_exp_f32_e32 v97, v97
	v_exp_f32_e32 v93, v93
	v_mad_u32_u24 v75, v167, s34, v75
	v_readlane_b32 s0, v254, 7
	v_lshl_add_u64 v[74:75], v[74:75], 0, s[54:55]
	v_readlane_b32 s1, v254, 8
	s_mov_b32 s69, s55
	s_lshl_b32 s54, s54, 1
	v_lshl_add_u64 v[88:89], v[74:75], 0, s[0:1]
	v_lshl_add_u64 v[74:75], v[164:165], 0, s[68:69]
	v_lshl_add_u64 v[74:75], v[74:75], 0, s[54:55]
	s_lshl_b32 s54, s0, 1
	v_pk_add_f32 v[102:103], v[100:101], v[86:87]
	v_pk_add_f32 v[104:105], v[68:69], v[78:79]
	v_pk_add_f32 v[106:107], v[96:97], v[92:93]
	v_pk_add_f32 v[108:109], v[72:73], v[82:83]
	v_pk_add_f32 v[110:111], v[94:95], v[84:85]
	v_pk_add_f32 v[112:113], v[66:67], v[76:77]
	v_pk_add_f32 v[114:115], v[98:99], v[90:91]
	v_pk_add_f32 v[116:117], v[70:71], v[80:81]
	v_pk_add_f32 v[110:111], v[112:113], v[110:111]
	v_pk_add_f32 v[114:115], v[116:117], v[114:115]
	v_pk_add_f32 v[106:107], v[108:109], v[106:107]
	v_pk_add_f32 v[102:103], v[104:105], v[102:103]
	s_cmp_lg_u32 0, -1
	v_pk_add_f32 v[102:103], v[102:103], v[106:107]
	v_pk_add_f32 v[104:105], v[110:111], v[114:115]
	s_cselect_b32 s0, 0, 0
	v_pk_add_f32 v[102:103], v[104:105], v[102:103]
	v_cvt_pk_bf16_f32 v66, v66, v67
	v_cvt_pk_bf16_f32 v67, v68, v69
	v_cvt_pk_bf16_f32 v68, v70, v71
	v_cvt_pk_bf16_f32 v69, v72, v73
	s_add_i32 s0, s0, 0x10400
	v_add_f32_e32 v0, v102, v103
	v_cvt_pk_bf16_f32 v70, v94, v95
	v_cvt_pk_bf16_f32 v71, v100, v101
	v_cvt_pk_bf16_f32 v72, v98, v99
	v_cvt_pk_bf16_f32 v73, v96, v97
	v_cvt_pk_bf16_f32 v76, v76, v77
	v_cvt_pk_bf16_f32 v77, v78, v79
	v_cvt_pk_bf16_f32 v78, v80, v81
	v_cvt_pk_bf16_f32 v79, v82, v83
	v_cvt_pk_bf16_f32 v80, v84, v85
	v_cvt_pk_bf16_f32 v81, v86, v87
	v_cvt_pk_bf16_f32 v82, v90, v91
	v_cvt_pk_bf16_f32 v83, v92, v93
	v_add_u32_e32 v102, s0, v163
	ds_read_b64_tr_b16 v[98:99], v102 offset:0
	ds_read_b64_tr_b16 v[100:101], v102 offset:0x200
	ds_read_b64_tr_b16 v[94:95], v102 offset:0x400
	ds_read_b64_tr_b16 v[96:97], v102 offset:0x600
	ds_read_b64_tr_b16 v[90:91], v102 offset:0x800
	ds_read_b64_tr_b16 v[92:93], v102 offset:0xa00
	ds_read_b64_tr_b16 v[84:85], v102 offset:0xc00
	ds_read_b64_tr_b16 v[86:87], v102 offset:0xe00
	s_waitcnt lgkmcnt(0)
	v_add_f32_e32 v0, v193, v0
	v_mfma_f32_32x32x16_bf16 v[50:65], v[98:101], v[66:69], v[50:65]
	v_lshl_add_u64 v[74:75], v[74:75], 0, s[54:55]
	s_mov_b64 s[0:1], 0x1000
	v_readlane_b32 s28, v254, 27
	s_movk_i32 s20, 0x600
	v_readlane_b32 s3, v254, 29
	v_readlane_b32 s29, v254, 28
	v_mov_b32_e32 v163, v1
	v_mfma_f32_32x32x16_bf16 v[50:65], v[94:97], v[70:73], v[50:65]
	v_mfma_f32_32x32x16_bf16 v[50:65], v[90:93], v[76:79], v[50:65]
	v_mfma_f32_32x32x16_bf16 v[50:65], v[84:87], v[80:83], v[50:65]
	ds_read_b64_tr_b16 v[98:99], v102 offset:0x1000
	ds_read_b64_tr_b16 v[100:101], v102 offset:0x1200
	ds_read_b64_tr_b16 v[94:95], v102 offset:0x1400
	ds_read_b64_tr_b16 v[96:97], v102 offset:0x1600
	ds_read_b64_tr_b16 v[90:91], v102 offset:0x1800
	ds_read_b64_tr_b16 v[92:93], v102 offset:0x1a00
	ds_read_b64_tr_b16 v[84:85], v102 offset:0x1c00
	ds_read_b64_tr_b16 v[86:87], v102 offset:0x1e00
	s_waitcnt lgkmcnt(0)
	s_nop 0
	v_mfma_f32_32x32x16_bf16 v[34:49], v[98:101], v[66:69], v[34:49]
	v_mfma_f32_32x32x16_bf16 v[34:49], v[94:97], v[70:73], v[34:49]
	v_mfma_f32_32x32x16_bf16 v[34:49], v[90:93], v[76:79], v[34:49]
	v_mfma_f32_32x32x16_bf16 v[34:49], v[84:87], v[80:83], v[34:49]
	ds_read_b64_tr_b16 v[98:99], v102 offset:0x2000
	ds_read_b64_tr_b16 v[100:101], v102 offset:0x2200
	ds_read_b64_tr_b16 v[94:95], v102 offset:0x2400
	ds_read_b64_tr_b16 v[96:97], v102 offset:0x2600
	ds_read_b64_tr_b16 v[90:91], v102 offset:0x2800
	ds_read_b64_tr_b16 v[92:93], v102 offset:0x2a00
	ds_read_b64_tr_b16 v[84:85], v102 offset:0x2c00
	ds_read_b64_tr_b16 v[86:87], v102 offset:0x2e00
	s_waitcnt lgkmcnt(0)
	s_nop 0
	v_mfma_f32_32x32x16_bf16 v[18:33], v[98:101], v[66:69], v[18:33]
	v_mfma_f32_32x32x16_bf16 v[18:33], v[94:97], v[70:73], v[18:33]
	v_mfma_f32_32x32x16_bf16 v[18:33], v[90:93], v[76:79], v[18:33]
	v_mfma_f32_32x32x16_bf16 v[18:33], v[84:87], v[80:83], v[18:33]
	ds_read_b64_tr_b16 v[98:99], v102 offset:0x3000
	ds_read_b64_tr_b16 v[100:101], v102 offset:0x3200
	ds_read_b64_tr_b16 v[94:95], v102 offset:0x3400
	ds_read_b64_tr_b16 v[96:97], v102 offset:0x3600
	ds_read_b64_tr_b16 v[90:91], v102 offset:0x3800
	ds_read_b64_tr_b16 v[92:93], v102 offset:0x3a00
	ds_read_b64_tr_b16 v[84:85], v102 offset:0x3c00
	ds_read_b64_tr_b16 v[86:87], v102 offset:0x3e00
	s_waitcnt lgkmcnt(0)
	s_waitcnt vmcnt(0)
	s_barrier
; DI float bf2f(unsigned b) { return __uint_as_float(b << 16); }
; template <int DQK, int W1, int DV, int VW, int MODE> ...
;     ...
;       pv_block<0>(o[0], bufa + vlane, pb);
;       if constexpr (NCB > 1) pv_block<1>(o[1], bufa + vlane, pb);
;       if constexpr (NCB > 2) pv_block<2>(o[2], bufa + vlane, pb);
;       if constexpr (NCB > 3) pv_block<3>(o[3], bufa + vlane, pb);
;     }
;     asm volatile("s_waitcnt vmcnt(0)" ::: "memory");
;     __syncthreads();
;   }
;   const float inv = __builtin_amdgcn_rcpf(xhalf_sum(l));
;   u32x2 ggv[NCB * 4];
; #pragma unroll
;   for (int cb = 0; cb < NCB; ++cb)
; #pragma unroll
;     for (int g = 0; g < 4; ++g) ggv[cb * 4 + g] = *(const u32x2*)(grow + 32 * cb + 8 * g + 4 * hi);
;   __builtin_amdgcn_sched_barrier(0);
; #pragma unroll
;   for (int cb = 0; cb < NCB; ++cb)
; #pragma unroll
;     for (int g = 0; g < 4; ++g) {
;       const int dv = 32 * cb + 8 * g + 4 * hi;
;       const u32x2 gg = ggv[cb * 4 + g];
;       float gv[4] = {bf2f(gg[0] & 0xffffu), bf2f(gg[0] >> 16), bf2f(gg[1] & 0xffffu), bf2f(gg[1] >> 16)};
;       float ov[4];
; #pragma unroll
;       for (int j = 0; j < 4; ++j) {
;         const float sg = gv[j] * __builtin_amdgcn_rcpf(1.f + __builtin_amdgcn_exp2f(-LOG2E * gv[j]));
;         ov[j] = o[cb][4 * g + j] * inv * sg;
;       }
;       *(unsigned*)((unsigned char*)yrow + dv) = pk4_fp8(ov[0] * Y_SCALE, ov[1] * Y_SCALE, ov[2] * Y_SCALE, ov[3] * Y_SCALE);
;       __builtin_amdgcn_sched_barrier(0);
;     }
	v_mfma_f32_32x32x16_bf16 v[2:17], v[98:101], v[66:69], v[2:17]
	v_mov_b32_e32 v66, v0
	s_nop 1
	v_permlane32_swap_b32_e32 v0, v66
	v_add_f32_e32 v102, v0, v66
	v_lshlrev_b32_e32 v0, 1, v162
	v_lshl_add_u64 v[66:67], v[74:75], 0, v[0:1]
	v_lshl_add_u64 v[98:99], v[66:67], 0, s[0:1]
	v_mfma_f32_32x32x16_bf16 v[2:17], v[94:97], v[70:73], v[2:17]
	s_movk_i32 s0, 0x1000
	v_add_co_u32_e32 v66, vcc, s0, v66
	v_rcp_f32_e32 v0, v102
	s_nop 0
	v_addc_co_u32_e32 v67, vcc, 0, v67, vcc
	v_mfma_f32_32x32x16_bf16 v[2:17], v[90:93], v[76:79], v[2:17]
	v_mfma_f32_32x32x16_bf16 v[2:17], v[84:87], v[80:83], v[2:17]
	v_bfe_i32 v211, v179, 5, 1
	v_mul_i32_i24_e32 v210, 24, v211
	v_lshl_add_u64 v[208:209], v[98:99], 0, v[210:211]
	global_load_dwordx2 v[100:101], v[66:67], off
	global_load_dwordx4 v[94:97], v[208:209], off offset:32
	global_load_dwordx4 v[90:93], v[208:209], off offset:64
	global_load_dwordx4 v[84:87], v[208:209], off offset:96
	global_load_dwordx4 v[80:83], v[208:209], off offset:128
	global_load_dwordx4 v[76:79], v[208:209], off offset:160
	global_load_dwordx4 v[72:75], v[208:209], off offset:192
	global_load_dwordx4 v[68:71], v[208:209], off offset:224
	global_load_dwordx2 v[66:67], v[98:99], off offset:240
	s_waitcnt vmcnt(8)
	v_lshlrev_b32_e32 v98, 16, v100
	v_mul_f32_e32 v102, 0xbfb8aa3b, v98
	v_exp_f32_e32 v102, v102
	v_and_b32_e32 v99, 0xffff0000, v100
	v_mul_f32_e32 v0, 0x41800000, v0
	v_mul_f32_e32 v50, v50, v0
	v_lshlrev_b32_e32 v100, 16, v101
	v_add_f32_e32 v102, 1.0, v102
	v_rcp_f32_e32 v102, v102
	v_mul_f32_e32 v51, v51, v0
	v_and_b32_e32 v101, 0xffff0000, v101
	v_mul_f32_e32 v52, v52, v0
	v_mul_f32_e32 v98, v102, v98
	v_mul_f32_e32 v50, v50, v98
	v_mul_f32_e32 v98, 0xbfb8aa3b, v99
	v_exp_f32_e32 v98, v98
	v_mul_f32_e32 v53, v53, v0
	v_med3_f32 v50, v50, s93, v223
	v_add_f32_e32 v98, 1.0, v98
	v_rcp_f32_e32 v98, v98
	s_nop 0
	v_mul_f32_e32 v98, v98, v99
	v_mul_f32_e32 v51, v51, v98
	v_mul_f32_e32 v98, 0xbfb8aa3b, v100
	v_exp_f32_e32 v98, v98
	s_nop 0
	v_med3_f32 v51, v51, s93, v223
	v_add_f32_e32 v98, 1.0, v98
	v_rcp_f32_e32 v98, v98
	s_nop 0
	v_mul_f32_e32 v98, v98, v100
	v_mul_f32_e32 v52, v52, v98
	v_mul_f32_e32 v98, 0xbfb8aa3b, v101
	v_exp_f32_e32 v98, v98
	s_nop 0
	v_add_f32_e32 v98, 1.0, v98
	v_rcp_f32_e32 v98, v98
	s_nop 0
	v_mul_f32_e32 v98, v98, v101
	v_mul_f32_e32 v53, v53, v98
	v_mov_b32_e32 v212, v1
	v_cvt_pk_fp8_f32 v212, v50, v51
	v_med3_f32 v50, v52, s93, v223
	v_med3_f32 v51, v53, s93, v223
	v_cvt_pk_fp8_f32 v212, v50, v51 op_sel:[0,0,1]
	v_lshl_add_u64 v[50:51], v[88:89], 0, v[162:163]
	s_waitcnt vmcnt(7)
	v_permlane32_swap_b32_e32 v94, v96
	v_permlane32_swap_b32_e32 v95, v97
	v_lshlrev_b32_e32 v52, 16, v96
	v_and_b32_e32 v53, 0xffff0000, v96
	v_mul_f32_e32 v96, 0xbfb8aa3b, v52
	v_exp_f32_e32 v96, v96
	v_mul_f32_e32 v54, v54, v0
	v_lshlrev_b32_e32 v88, 16, v97
	v_and_b32_e32 v89, 0xffff0000, v97
	v_add_f32_e32 v96, 1.0, v96
	v_rcp_f32_e32 v96, v96
	s_nop 0
	v_mul_f32_e32 v52, v96, v52
	v_mul_f32_e32 v52, v54, v52
	v_mul_f32_e32 v54, 0xbfb8aa3b, v53
	v_exp_f32_e32 v54, v54
	s_nop 0
	v_med3_f32 v52, v52, s93, v223
	v_add_f32_e32 v54, 1.0, v54
	v_rcp_f32_e32 v54, v54
	s_nop 0
	v_mul_f32_e32 v53, v54, v53
	v_mul_f32_e32 v54, v55, v0
	v_mul_f32_e32 v53, v54, v53
	v_mul_f32_e32 v54, 0xbfb8aa3b, v88
	v_exp_f32_e32 v54, v54
	v_mul_f32_e32 v55, v56, v0
	v_mul_f32_e32 v56, v57, v0
	v_add_f32_e32 v54, 1.0, v54
	v_rcp_f32_e32 v54, v54
	v_med3_f32 v53, v53, s93, v223
	v_mul_f32_e32 v54, v54, v88
	v_mul_f32_e32 v54, v55, v54
	v_mul_f32_e32 v55, 0xbfb8aa3b, v89
	v_exp_f32_e32 v55, v55
	s_nop 0
	v_add_f32_e32 v55, 1.0, v55
	v_rcp_f32_e32 v55, v55
	s_nop 0
	v_mul_f32_e32 v55, v55, v89
	v_mul_f32_e32 v55, v56, v55
	v_mov_b32_e32 v214, v1
	v_cvt_pk_fp8_f32 v214, v52, v53
	v_med3_f32 v52, v54, s93, v223
	v_med3_f32 v53, v55, s93, v223
	v_cvt_pk_fp8_f32 v214, v52, v53 op_sel:[0,0,1]
	s_waitcnt vmcnt(7)
	v_lshlrev_b32_e32 v52, 16, v94
	v_mul_f32_e32 v56, 0xbfb8aa3b, v52
	v_exp_f32_e32 v56, v56
	v_and_b32_e32 v53, 0xffff0000, v94
	v_lshlrev_b32_e32 v54, 16, v95
	v_and_b32_e32 v55, 0xffff0000, v95
	v_add_f32_e32 v56, 1.0, v56
	v_rcp_f32_e32 v56, v56
	s_nop 0
	v_mul_f32_e32 v52, v56, v52
	v_mul_f32_e32 v56, v58, v0
	v_mul_f32_e32 v52, v56, v52
	v_mul_f32_e32 v56, 0xbfb8aa3b, v53
	v_exp_f32_e32 v56, v56
	s_nop 0
	v_med3_f32 v52, v52, s93, v223
	v_add_f32_e32 v56, 1.0, v56
	v_rcp_f32_e32 v56, v56
	s_nop 0
	v_mul_f32_e32 v53, v56, v53
	v_mul_f32_e32 v56, v59, v0
	v_mul_f32_e32 v53, v56, v53
	v_mul_f32_e32 v56, 0xbfb8aa3b, v54
	v_exp_f32_e32 v56, v56
	s_nop 0
	v_med3_f32 v53, v53, s93, v223
	v_add_f32_e32 v56, 1.0, v56
	v_rcp_f32_e32 v56, v56
	s_nop 0
	v_mul_f32_e32 v54, v56, v54
	v_mul_f32_e32 v56, v60, v0
	v_mul_f32_e32 v54, v56, v54
	v_mul_f32_e32 v56, 0xbfb8aa3b, v55
	v_exp_f32_e32 v56, v56
	s_nop 0
	v_add_f32_e32 v56, 1.0, v56
	v_rcp_f32_e32 v56, v56
	s_nop 0
	v_mul_f32_e32 v55, v56, v55
	v_mul_f32_e32 v56, v61, v0
	v_mul_f32_e32 v55, v56, v55
	v_mov_b32_e32 v213, v1
	v_cvt_pk_fp8_f32 v213, v52, v53
	v_med3_f32 v52, v54, s93, v223
	v_med3_f32 v53, v55, s93, v223
	v_cvt_pk_fp8_f32 v213, v52, v53 op_sel:[0,0,1]
	s_waitcnt vmcnt(6)
; DI float bf2f(unsigned b) { return __uint_as_float(b << 16); }
; template <int DQK, int W1, int DV, int VW, int MODE> ...
;     ...
; #pragma unroll
;   for (int cb = 0; cb < NCB; ++cb)
; #pragma unroll
;     for (int g = 0; g < 4; ++g) {
;       const int dv = 32 * cb + 8 * g + 4 * hi;
;       const u32x2 gg = ggv[cb * 4 + g];
;       float gv[4] = {bf2f(gg[0] & 0xffffu), bf2f(gg[0] >> 16), bf2f(gg[1] & 0xffffu), bf2f(gg[1] >> 16)};
;       float ov[4];
; #pragma unroll
;       for (int j = 0; j < 4; ++j) {
;         const float sg = gv[j] * __builtin_amdgcn_rcpf(1.f + __builtin_amdgcn_exp2f(-LOG2E * gv[j]));
;         ov[j] = o[cb][4 * g + j] * inv * sg;
;       }
;       *(unsigned*)((unsigned char*)yrow + dv) = pk4_fp8(ov[0] * Y_SCALE, ov[1] * Y_SCALE, ov[2] * Y_SCALE, ov[3] * Y_SCALE);
;       __builtin_amdgcn_sched_barrier(0);
;     }
	v_permlane32_swap_b32_e32 v90, v92
	v_permlane32_swap_b32_e32 v91, v93
	v_lshlrev_b32_e32 v52, 16, v92
	v_mul_f32_e32 v56, 0xbfb8aa3b, v52
	v_exp_f32_e32 v56, v56
	v_and_b32_e32 v53, 0xffff0000, v92
	v_lshlrev_b32_e32 v54, 16, v93
	v_and_b32_e32 v55, 0xffff0000, v93
	v_add_f32_e32 v56, 1.0, v56
	v_rcp_f32_e32 v56, v56
	s_nop 0
	v_mul_f32_e32 v52, v56, v52
	v_mul_f32_e32 v56, v62, v0
	v_mul_f32_e32 v52, v56, v52
	v_mul_f32_e32 v56, 0xbfb8aa3b, v53
	v_exp_f32_e32 v56, v56
	s_nop 0
	v_med3_f32 v52, v52, s93, v223
	v_add_f32_e32 v56, 1.0, v56
	v_rcp_f32_e32 v56, v56
	s_nop 0
	v_mul_f32_e32 v53, v56, v53
	v_mul_f32_e32 v56, v63, v0
	v_mul_f32_e32 v53, v56, v53
	v_mul_f32_e32 v56, 0xbfb8aa3b, v54
	v_exp_f32_e32 v56, v56
	s_nop 0
	v_med3_f32 v53, v53, s93, v223
	v_add_f32_e32 v56, 1.0, v56
	v_rcp_f32_e32 v56, v56
	s_nop 0
	v_mul_f32_e32 v54, v56, v54
	v_mul_f32_e32 v56, v64, v0
	v_mul_f32_e32 v54, v56, v54
	v_mul_f32_e32 v56, 0xbfb8aa3b, v55
	v_exp_f32_e32 v56, v56
	s_nop 0
	v_add_f32_e32 v56, 1.0, v56
	v_rcp_f32_e32 v56, v56
	s_nop 0
	v_mul_f32_e32 v55, v56, v55
	v_mul_f32_e32 v56, v65, v0
	v_mul_f32_e32 v55, v56, v55
	v_mov_b32_e32 v215, v1
	v_cvt_pk_fp8_f32 v215, v52, v53
	v_med3_f32 v52, v54, s93, v223
	v_med3_f32 v53, v55, s93, v223
	v_cvt_pk_fp8_f32 v215, v52, v53 op_sel:[0,0,1]
	v_and_b32_e32 v242, 32, v179
	v_lshrrev_b32_e32 v242, 3, v242
	v_lshl_add_u32 v242, v242, 1, v242
	v_mov_b32_e32 v243, 0
	v_lshl_add_u64 v[216:217], v[50:51], 0, v[242:243]
	s_nop 1
	v_permlane32_swap_b32_e32 v212, v213
	v_permlane32_swap_b32_e32 v214, v215
	global_store_dwordx4 v[216:217], v[212:215], off offset:2048
	s_waitcnt vmcnt(7)
	v_lshlrev_b32_e32 v52, 16, v90
	v_mul_f32_e32 v56, 0xbfb8aa3b, v52
	v_exp_f32_e32 v56, v56
	v_and_b32_e32 v53, 0xffff0000, v90
	v_mul_f32_e32 v34, v34, v0
	v_lshlrev_b32_e32 v54, 16, v91
	v_add_f32_e32 v56, 1.0, v56
	v_rcp_f32_e32 v56, v56
	v_mul_f32_e32 v35, v35, v0
	v_and_b32_e32 v55, 0xffff0000, v91
	v_mul_f32_e32 v36, v36, v0
	v_mul_f32_e32 v52, v56, v52
	v_mul_f32_e32 v34, v34, v52
	v_mul_f32_e32 v52, 0xbfb8aa3b, v53
	v_exp_f32_e32 v52, v52
	v_mul_f32_e32 v37, v37, v0
	v_med3_f32 v34, v34, s93, v223
	v_add_f32_e32 v52, 1.0, v52
	v_rcp_f32_e32 v52, v52
	s_nop 0
	v_mul_f32_e32 v52, v52, v53
	v_mul_f32_e32 v35, v35, v52
	v_mul_f32_e32 v52, 0xbfb8aa3b, v54
	v_exp_f32_e32 v52, v52
	s_nop 0
	v_med3_f32 v35, v35, s93, v223
	v_add_f32_e32 v52, 1.0, v52
	v_rcp_f32_e32 v52, v52
	s_nop 0
	v_mul_f32_e32 v52, v52, v54
	v_mul_f32_e32 v36, v36, v52
	v_mul_f32_e32 v52, 0xbfb8aa3b, v55
	v_exp_f32_e32 v52, v52
	s_nop 0
	v_add_f32_e32 v52, 1.0, v52
	v_rcp_f32_e32 v52, v52
	s_nop 0
	v_mul_f32_e32 v52, v52, v55
	v_mul_f32_e32 v37, v37, v52
	v_mov_b32_e32 v212, v1
	v_cvt_pk_fp8_f32 v212, v34, v35
	v_med3_f32 v34, v36, s93, v223
	v_med3_f32 v35, v37, s93, v223
	v_cvt_pk_fp8_f32 v212, v34, v35 op_sel:[0,0,1]
	s_waitcnt vmcnt(6)
	v_permlane32_swap_b32_e32 v84, v86
	v_permlane32_swap_b32_e32 v85, v87
	v_lshlrev_b32_e32 v34, 16, v86
	v_mul_f32_e32 v52, 0xbfb8aa3b, v34
	v_exp_f32_e32 v52, v52
	v_and_b32_e32 v35, 0xffff0000, v86
	v_mul_f32_e32 v38, v38, v0
	v_lshlrev_b32_e32 v36, 16, v87
	v_add_f32_e32 v52, 1.0, v52
	v_rcp_f32_e32 v52, v52
	v_and_b32_e32 v37, 0xffff0000, v87
	v_mul_f32_e32 v34, v52, v34
	v_mul_f32_e32 v34, v38, v34
	v_mul_f32_e32 v38, 0xbfb8aa3b, v35
	v_exp_f32_e32 v38, v38
	s_nop 0
	v_med3_f32 v34, v34, s93, v223
	v_add_f32_e32 v38, 1.0, v38
	v_rcp_f32_e32 v38, v38
	s_nop 0
	v_mul_f32_e32 v35, v38, v35
	v_mul_f32_e32 v38, v39, v0
	v_mul_f32_e32 v35, v38, v35
	v_mul_f32_e32 v38, 0xbfb8aa3b, v36
	v_exp_f32_e32 v38, v38
	s_nop 0
	v_med3_f32 v35, v35, s93, v223
	v_add_f32_e32 v38, 1.0, v38
	v_rcp_f32_e32 v38, v38
	s_nop 0
	v_mul_f32_e32 v36, v38, v36
	v_mul_f32_e32 v38, v40, v0
	v_mul_f32_e32 v36, v38, v36
	v_mul_f32_e32 v38, 0xbfb8aa3b, v37
	v_exp_f32_e32 v38, v38
	s_nop 0
	v_add_f32_e32 v38, 1.0, v38
	v_rcp_f32_e32 v38, v38
	s_nop 0
	v_mul_f32_e32 v37, v38, v37
	v_mul_f32_e32 v38, v41, v0
	v_mul_f32_e32 v37, v38, v37
	v_mov_b32_e32 v214, v1
	v_cvt_pk_fp8_f32 v214, v34, v35
	v_med3_f32 v34, v36, s93, v223
	v_med3_f32 v35, v37, s93, v223
	v_cvt_pk_fp8_f32 v214, v34, v35 op_sel:[0,0,1]
	s_waitcnt vmcnt(6)
	v_lshlrev_b32_e32 v34, 16, v84
	v_mul_f32_e32 v38, 0xbfb8aa3b, v34
	v_exp_f32_e32 v38, v38
	v_and_b32_e32 v35, 0xffff0000, v84
	v_lshlrev_b32_e32 v36, 16, v85
	v_and_b32_e32 v37, 0xffff0000, v85
	v_add_f32_e32 v38, 1.0, v38
	v_rcp_f32_e32 v38, v38
	s_nop 0
	v_mul_f32_e32 v34, v38, v34
	v_mul_f32_e32 v38, v42, v0
	v_mul_f32_e32 v34, v38, v34
	v_mul_f32_e32 v38, 0xbfb8aa3b, v35
	v_exp_f32_e32 v38, v38
	s_nop 0
	v_med3_f32 v34, v34, s93, v223
	v_add_f32_e32 v38, 1.0, v38
	v_rcp_f32_e32 v38, v38
	s_nop 0
	v_mul_f32_e32 v35, v38, v35
	v_mul_f32_e32 v38, v43, v0
	v_mul_f32_e32 v35, v38, v35
	v_mul_f32_e32 v38, 0xbfb8aa3b, v36
	v_exp_f32_e32 v38, v38
	s_nop 0
	v_med3_f32 v35, v35, s93, v223
	v_add_f32_e32 v38, 1.0, v38
	v_rcp_f32_e32 v38, v38
	s_nop 0
	v_mul_f32_e32 v36, v38, v36
	v_mul_f32_e32 v38, v44, v0
	v_mul_f32_e32 v36, v38, v36
	v_mul_f32_e32 v38, 0xbfb8aa3b, v37
	v_exp_f32_e32 v38, v38
	s_nop 0
	v_add_f32_e32 v38, 1.0, v38
	v_rcp_f32_e32 v38, v38
	s_nop 0
	v_mul_f32_e32 v37, v38, v37
	v_mul_f32_e32 v38, v45, v0
	v_mul_f32_e32 v37, v38, v37
	v_mov_b32_e32 v213, v1
	v_cvt_pk_fp8_f32 v213, v34, v35
	v_med3_f32 v34, v36, s93, v223
	v_med3_f32 v35, v37, s93, v223
	v_cvt_pk_fp8_f32 v213, v34, v35 op_sel:[0,0,1]
	s_waitcnt vmcnt(5)
; DI float bf2f(unsigned b) { return __uint_as_float(b << 16); }
; template <int DQK, int W1, int DV, int VW, int MODE> ...
;     ...
; #pragma unroll
;   for (int cb = 0; cb < NCB; ++cb)
; #pragma unroll
;     for (int g = 0; g < 4; ++g) {
;       const int dv = 32 * cb + 8 * g + 4 * hi;
;       const u32x2 gg = ggv[cb * 4 + g];
;       float gv[4] = {bf2f(gg[0] & 0xffffu), bf2f(gg[0] >> 16), bf2f(gg[1] & 0xffffu), bf2f(gg[1] >> 16)};
;       float ov[4];
; #pragma unroll
;       for (int j = 0; j < 4; ++j) {
;         const float sg = gv[j] * __builtin_amdgcn_rcpf(1.f + __builtin_amdgcn_exp2f(-LOG2E * gv[j]));
;         ov[j] = o[cb][4 * g + j] * inv * sg;
;       }
;       *(unsigned*)((unsigned char*)yrow + dv) = pk4_fp8(ov[0] * Y_SCALE, ov[1] * Y_SCALE, ov[2] * Y_SCALE, ov[3] * Y_SCALE);
;       __builtin_amdgcn_sched_barrier(0);
;     }
	v_permlane32_swap_b32_e32 v80, v82
	v_permlane32_swap_b32_e32 v81, v83
	v_lshlrev_b32_e32 v34, 16, v82
	v_mul_f32_e32 v38, 0xbfb8aa3b, v34
	v_exp_f32_e32 v38, v38
	v_and_b32_e32 v35, 0xffff0000, v82
	v_lshlrev_b32_e32 v36, 16, v83
	v_and_b32_e32 v37, 0xffff0000, v83
	v_add_f32_e32 v38, 1.0, v38
	v_rcp_f32_e32 v38, v38
	s_nop 0
	v_mul_f32_e32 v34, v38, v34
	v_mul_f32_e32 v38, v46, v0
	v_mul_f32_e32 v34, v38, v34
	v_mul_f32_e32 v38, 0xbfb8aa3b, v35
	v_exp_f32_e32 v38, v38
	s_nop 0
	v_med3_f32 v34, v34, s93, v223
	v_add_f32_e32 v38, 1.0, v38
	v_rcp_f32_e32 v38, v38
	s_nop 0
	v_mul_f32_e32 v35, v38, v35
	v_mul_f32_e32 v38, v47, v0
	v_mul_f32_e32 v35, v38, v35
	v_mul_f32_e32 v38, 0xbfb8aa3b, v36
	v_exp_f32_e32 v38, v38
	s_nop 0
	v_med3_f32 v35, v35, s93, v223
	v_add_f32_e32 v38, 1.0, v38
	v_rcp_f32_e32 v38, v38
	s_nop 0
	v_mul_f32_e32 v36, v38, v36
	v_mul_f32_e32 v38, v48, v0
	v_mul_f32_e32 v36, v38, v36
	v_mul_f32_e32 v38, 0xbfb8aa3b, v37
	v_exp_f32_e32 v38, v38
	s_nop 0
	v_add_f32_e32 v38, 1.0, v38
	v_rcp_f32_e32 v38, v38
	s_nop 0
	v_mul_f32_e32 v37, v38, v37
	v_mul_f32_e32 v38, v49, v0
	v_mul_f32_e32 v37, v38, v37
	v_mov_b32_e32 v215, v1
	v_cvt_pk_fp8_f32 v215, v34, v35
	v_med3_f32 v34, v36, s93, v223
	v_med3_f32 v35, v37, s93, v223
	v_cvt_pk_fp8_f32 v215, v34, v35 op_sel:[0,0,1]
	s_nop 1
	v_permlane32_swap_b32_e32 v212, v213
	v_permlane32_swap_b32_e32 v214, v215
	global_store_dwordx4 v[216:217], v[212:215], off offset:2080
	s_waitcnt vmcnt(6)
	v_lshlrev_b32_e32 v34, 16, v80
	v_mul_f32_e32 v38, 0xbfb8aa3b, v34
	v_exp_f32_e32 v38, v38
	v_and_b32_e32 v35, 0xffff0000, v80
	v_mul_f32_e32 v18, v18, v0
	v_lshlrev_b32_e32 v36, 16, v81
	v_add_f32_e32 v38, 1.0, v38
	v_rcp_f32_e32 v38, v38
	v_mul_f32_e32 v19, v19, v0
	v_and_b32_e32 v37, 0xffff0000, v81
	v_mul_f32_e32 v20, v20, v0
	v_mul_f32_e32 v34, v38, v34
	v_mul_f32_e32 v18, v18, v34
	v_mul_f32_e32 v34, 0xbfb8aa3b, v35
	v_exp_f32_e32 v34, v34
	v_mul_f32_e32 v21, v21, v0
	v_med3_f32 v18, v18, s93, v223
	v_add_f32_e32 v34, 1.0, v34
	v_rcp_f32_e32 v34, v34
	s_nop 0
	v_mul_f32_e32 v34, v34, v35
	v_mul_f32_e32 v19, v19, v34
	v_mul_f32_e32 v34, 0xbfb8aa3b, v36
	v_exp_f32_e32 v34, v34
	s_nop 0
	v_med3_f32 v19, v19, s93, v223
	v_add_f32_e32 v34, 1.0, v34
	v_rcp_f32_e32 v34, v34
	s_nop 0
	v_mul_f32_e32 v34, v34, v36
	v_mul_f32_e32 v20, v20, v34
	v_mul_f32_e32 v34, 0xbfb8aa3b, v37
	v_exp_f32_e32 v34, v34
	s_nop 0
	v_add_f32_e32 v34, 1.0, v34
	v_rcp_f32_e32 v34, v34
	s_nop 0
	v_mul_f32_e32 v34, v34, v37
	v_mul_f32_e32 v21, v21, v34
	v_mov_b32_e32 v212, v1
	v_cvt_pk_fp8_f32 v212, v18, v19
	v_med3_f32 v18, v20, s93, v223
	v_med3_f32 v19, v21, s93, v223
	v_cvt_pk_fp8_f32 v212, v18, v19 op_sel:[0,0,1]
	s_waitcnt vmcnt(5)
	v_permlane32_swap_b32_e32 v76, v78
	v_permlane32_swap_b32_e32 v77, v79
	v_lshlrev_b32_e32 v18, 16, v78
	v_mul_f32_e32 v34, 0xbfb8aa3b, v18
	v_exp_f32_e32 v34, v34
	v_and_b32_e32 v19, 0xffff0000, v78
	v_mul_f32_e32 v22, v22, v0
	v_lshlrev_b32_e32 v20, 16, v79
	v_add_f32_e32 v34, 1.0, v34
	v_rcp_f32_e32 v34, v34
	v_and_b32_e32 v21, 0xffff0000, v79
	v_mul_f32_e32 v18, v34, v18
	v_mul_f32_e32 v18, v22, v18
	v_mul_f32_e32 v22, 0xbfb8aa3b, v19
	v_exp_f32_e32 v22, v22
	s_nop 0
	v_med3_f32 v18, v18, s93, v223
	v_add_f32_e32 v22, 1.0, v22
	v_rcp_f32_e32 v22, v22
	s_nop 0
	v_mul_f32_e32 v19, v22, v19
	v_mul_f32_e32 v22, v23, v0
	v_mul_f32_e32 v19, v22, v19
	v_mul_f32_e32 v22, 0xbfb8aa3b, v20
	v_exp_f32_e32 v22, v22
	s_nop 0
	v_med3_f32 v19, v19, s93, v223
	v_add_f32_e32 v22, 1.0, v22
	v_rcp_f32_e32 v22, v22
	s_nop 0
	v_mul_f32_e32 v20, v22, v20
	v_mul_f32_e32 v22, v24, v0
	v_mul_f32_e32 v20, v22, v20
	v_mul_f32_e32 v22, 0xbfb8aa3b, v21
	v_exp_f32_e32 v22, v22
	s_nop 0
	v_add_f32_e32 v22, 1.0, v22
	v_rcp_f32_e32 v22, v22
	s_nop 0
	v_mul_f32_e32 v21, v22, v21
	v_mul_f32_e32 v22, v25, v0
	v_mul_f32_e32 v21, v22, v21
	v_mov_b32_e32 v214, v1
	v_cvt_pk_fp8_f32 v214, v18, v19
	v_med3_f32 v18, v20, s93, v223
	v_med3_f32 v19, v21, s93, v223
	v_cvt_pk_fp8_f32 v214, v18, v19 op_sel:[0,0,1]
	s_waitcnt vmcnt(5)
	v_lshlrev_b32_e32 v18, 16, v76
	v_mul_f32_e32 v22, 0xbfb8aa3b, v18
	v_exp_f32_e32 v22, v22
	v_and_b32_e32 v19, 0xffff0000, v76
	v_lshlrev_b32_e32 v20, 16, v77
	v_and_b32_e32 v21, 0xffff0000, v77
	v_add_f32_e32 v22, 1.0, v22
	v_rcp_f32_e32 v22, v22
	s_nop 0
	v_mul_f32_e32 v18, v22, v18
	v_mul_f32_e32 v22, v26, v0
	v_mul_f32_e32 v18, v22, v18
	v_mul_f32_e32 v22, 0xbfb8aa3b, v19
	v_exp_f32_e32 v22, v22
	s_nop 0
	v_med3_f32 v18, v18, s93, v223
	v_add_f32_e32 v22, 1.0, v22
	v_rcp_f32_e32 v22, v22
	s_nop 0
	v_mul_f32_e32 v19, v22, v19
	v_mul_f32_e32 v22, v27, v0
	v_mul_f32_e32 v19, v22, v19
	v_mul_f32_e32 v22, 0xbfb8aa3b, v20
	v_exp_f32_e32 v22, v22
	s_nop 0
	v_med3_f32 v19, v19, s93, v223
	v_add_f32_e32 v22, 1.0, v22
	v_rcp_f32_e32 v22, v22
	s_nop 0
	v_mul_f32_e32 v20, v22, v20
	v_mul_f32_e32 v22, v28, v0
	v_mul_f32_e32 v20, v22, v20
	v_mul_f32_e32 v22, 0xbfb8aa3b, v21
	v_exp_f32_e32 v22, v22
	s_nop 0
	v_add_f32_e32 v22, 1.0, v22
	v_rcp_f32_e32 v22, v22
	s_nop 0
	v_mul_f32_e32 v21, v22, v21
	v_mul_f32_e32 v22, v29, v0
	v_mul_f32_e32 v21, v22, v21
	v_mov_b32_e32 v213, v1
	v_cvt_pk_fp8_f32 v213, v18, v19
	v_med3_f32 v18, v20, s93, v223
	v_med3_f32 v19, v21, s93, v223
	v_cvt_pk_fp8_f32 v213, v18, v19 op_sel:[0,0,1]
	s_waitcnt vmcnt(4)
; DI float bf2f(unsigned b) { return __uint_as_float(b << 16); }
; template <int DQK, int W1, int DV, int VW, int MODE> ...
;     ...
; #pragma unroll
;   for (int cb = 0; cb < NCB; ++cb)
; #pragma unroll
;     for (int g = 0; g < 4; ++g) {
;       const int dv = 32 * cb + 8 * g + 4 * hi;
;       const u32x2 gg = ggv[cb * 4 + g];
;       float gv[4] = {bf2f(gg[0] & 0xffffu), bf2f(gg[0] >> 16), bf2f(gg[1] & 0xffffu), bf2f(gg[1] >> 16)};
;       float ov[4];
; #pragma unroll
;       for (int j = 0; j < 4; ++j) {
;         const float sg = gv[j] * __builtin_amdgcn_rcpf(1.f + __builtin_amdgcn_exp2f(-LOG2E * gv[j]));
;         ov[j] = o[cb][4 * g + j] * inv * sg;
;       }
;       *(unsigned*)((unsigned char*)yrow + dv) = pk4_fp8(ov[0] * Y_SCALE, ov[1] * Y_SCALE, ov[2] * Y_SCALE, ov[3] * Y_SCALE);
;       __builtin_amdgcn_sched_barrier(0);
;     }
	v_permlane32_swap_b32_e32 v72, v74
	v_permlane32_swap_b32_e32 v73, v75
	v_lshlrev_b32_e32 v18, 16, v74
	v_mul_f32_e32 v22, 0xbfb8aa3b, v18
	v_exp_f32_e32 v22, v22
	v_and_b32_e32 v19, 0xffff0000, v74
	v_lshlrev_b32_e32 v20, 16, v75
	v_and_b32_e32 v21, 0xffff0000, v75
	v_add_f32_e32 v22, 1.0, v22
	v_rcp_f32_e32 v22, v22
	s_nop 0
	v_mul_f32_e32 v18, v22, v18
	v_mul_f32_e32 v22, v30, v0
	v_mul_f32_e32 v18, v22, v18
	v_mul_f32_e32 v22, 0xbfb8aa3b, v19
	v_exp_f32_e32 v22, v22
	s_nop 0
	v_med3_f32 v18, v18, s93, v223
	v_add_f32_e32 v22, 1.0, v22
	v_rcp_f32_e32 v22, v22
	s_nop 0
	v_mul_f32_e32 v19, v22, v19
	v_mul_f32_e32 v22, v31, v0
	v_mul_f32_e32 v19, v22, v19
	v_mul_f32_e32 v22, 0xbfb8aa3b, v20
	v_exp_f32_e32 v22, v22
	s_nop 0
	v_med3_f32 v19, v19, s93, v223
	v_add_f32_e32 v22, 1.0, v22
	v_rcp_f32_e32 v22, v22
	s_nop 0
	v_mul_f32_e32 v20, v22, v20
	v_mul_f32_e32 v22, v32, v0
	v_mul_f32_e32 v20, v22, v20
	v_mul_f32_e32 v22, 0xbfb8aa3b, v21
	v_exp_f32_e32 v22, v22
	s_nop 0
	v_add_f32_e32 v22, 1.0, v22
	v_rcp_f32_e32 v22, v22
	s_nop 0
	v_mul_f32_e32 v21, v22, v21
	v_mul_f32_e32 v22, v33, v0
	v_mul_f32_e32 v21, v22, v21
	v_mov_b32_e32 v215, v1
	v_cvt_pk_fp8_f32 v215, v18, v19
	v_med3_f32 v18, v20, s93, v223
	v_med3_f32 v19, v21, s93, v223
	v_cvt_pk_fp8_f32 v215, v18, v19 op_sel:[0,0,1]
	s_nop 1
	v_permlane32_swap_b32_e32 v212, v213
	v_permlane32_swap_b32_e32 v214, v215
	global_store_dwordx4 v[216:217], v[212:215], off offset:2112
	s_waitcnt vmcnt(5)
	v_lshlrev_b32_e32 v18, 16, v72
	v_mul_f32_e32 v22, 0xbfb8aa3b, v18
	v_exp_f32_e32 v22, v22
	v_and_b32_e32 v19, 0xffff0000, v72
	v_mul_f32_e32 v2, v2, v0
	v_lshlrev_b32_e32 v20, 16, v73
	v_add_f32_e32 v22, 1.0, v22
	v_rcp_f32_e32 v22, v22
	v_mul_f32_e32 v3, v3, v0
	v_and_b32_e32 v21, 0xffff0000, v73
	v_mul_f32_e32 v4, v4, v0
	v_mul_f32_e32 v18, v22, v18
	v_mul_f32_e32 v2, v2, v18
	v_mul_f32_e32 v18, 0xbfb8aa3b, v19
	v_exp_f32_e32 v18, v18
	v_mul_f32_e32 v5, v5, v0
	v_med3_f32 v2, v2, s93, v223
	v_add_f32_e32 v18, 1.0, v18
	v_rcp_f32_e32 v18, v18
	s_nop 0
	v_mul_f32_e32 v18, v18, v19
	v_mul_f32_e32 v3, v3, v18
	v_mul_f32_e32 v18, 0xbfb8aa3b, v20
	v_exp_f32_e32 v18, v18
	s_nop 0
	v_med3_f32 v3, v3, s93, v223
	v_add_f32_e32 v18, 1.0, v18
	v_rcp_f32_e32 v18, v18
	s_nop 0
	v_mul_f32_e32 v18, v18, v20
	v_mul_f32_e32 v4, v4, v18
	v_mul_f32_e32 v18, 0xbfb8aa3b, v21
	v_exp_f32_e32 v18, v18
	s_nop 0
	v_add_f32_e32 v18, 1.0, v18
	v_rcp_f32_e32 v18, v18
	s_nop 0
	v_mul_f32_e32 v18, v18, v21
	v_mul_f32_e32 v5, v5, v18
	v_mov_b32_e32 v212, v1
	v_cvt_pk_fp8_f32 v212, v2, v3
	v_med3_f32 v2, v4, s93, v223
	v_med3_f32 v3, v5, s93, v223
	v_cvt_pk_fp8_f32 v212, v2, v3 op_sel:[0,0,1]
	s_waitcnt vmcnt(4)
	v_permlane32_swap_b32_e32 v68, v70
	v_permlane32_swap_b32_e32 v69, v71
	v_lshlrev_b32_e32 v2, 16, v70
	v_mul_f32_e32 v18, 0xbfb8aa3b, v2
	v_exp_f32_e32 v18, v18
	v_and_b32_e32 v3, 0xffff0000, v70
	v_mul_f32_e32 v6, v6, v0
	v_lshlrev_b32_e32 v4, 16, v71
	v_add_f32_e32 v18, 1.0, v18
	v_rcp_f32_e32 v18, v18
	v_and_b32_e32 v5, 0xffff0000, v71
	v_mul_f32_e32 v2, v18, v2
	v_mul_f32_e32 v2, v6, v2
	v_mul_f32_e32 v6, 0xbfb8aa3b, v3
	v_exp_f32_e32 v6, v6
	s_nop 0
	v_med3_f32 v2, v2, s93, v223
	v_add_f32_e32 v6, 1.0, v6
	v_rcp_f32_e32 v6, v6
	s_nop 0
	v_mul_f32_e32 v3, v6, v3
	v_mul_f32_e32 v6, v7, v0
	v_mul_f32_e32 v3, v6, v3
	v_mul_f32_e32 v6, 0xbfb8aa3b, v4
	v_exp_f32_e32 v6, v6
	s_nop 0
	v_med3_f32 v3, v3, s93, v223
	v_add_f32_e32 v6, 1.0, v6
	v_rcp_f32_e32 v6, v6
	s_nop 0
	v_mul_f32_e32 v4, v6, v4
	v_mul_f32_e32 v6, v8, v0
	v_mul_f32_e32 v4, v6, v4
	v_mul_f32_e32 v6, 0xbfb8aa3b, v5
	v_exp_f32_e32 v6, v6
	s_nop 0
	v_add_f32_e32 v6, 1.0, v6
	v_rcp_f32_e32 v6, v6
	s_nop 0
	v_mul_f32_e32 v5, v6, v5
	v_mul_f32_e32 v6, v9, v0
	v_mul_f32_e32 v5, v6, v5
	v_mov_b32_e32 v214, v1
	v_cvt_pk_fp8_f32 v214, v2, v3
	v_med3_f32 v2, v4, s93, v223
	v_med3_f32 v3, v5, s93, v223
	v_cvt_pk_fp8_f32 v214, v2, v3 op_sel:[0,0,1]
	s_waitcnt vmcnt(4)
	v_lshlrev_b32_e32 v2, 16, v68
	v_mul_f32_e32 v6, 0xbfb8aa3b, v2
	v_exp_f32_e32 v6, v6
	v_and_b32_e32 v3, 0xffff0000, v68
	v_lshlrev_b32_e32 v4, 16, v69
	v_and_b32_e32 v5, 0xffff0000, v69
	v_add_f32_e32 v6, 1.0, v6
	v_rcp_f32_e32 v6, v6
	s_nop 0
	v_mul_f32_e32 v2, v6, v2
	v_mul_f32_e32 v6, v10, v0
	v_mul_f32_e32 v2, v6, v2
	v_mul_f32_e32 v6, 0xbfb8aa3b, v3
	v_exp_f32_e32 v6, v6
	s_nop 0
	v_med3_f32 v2, v2, s93, v223
	v_add_f32_e32 v6, 1.0, v6
	v_rcp_f32_e32 v6, v6
	s_nop 0
	v_mul_f32_e32 v3, v6, v3
	v_mul_f32_e32 v6, v11, v0
	v_mul_f32_e32 v3, v6, v3
	v_mul_f32_e32 v6, 0xbfb8aa3b, v4
	v_exp_f32_e32 v6, v6
	s_nop 0
	v_med3_f32 v3, v3, s93, v223
	v_add_f32_e32 v6, 1.0, v6
	v_rcp_f32_e32 v6, v6
	s_nop 0
	v_mul_f32_e32 v4, v6, v4
	v_mul_f32_e32 v6, v12, v0
	v_mul_f32_e32 v4, v6, v4
	v_mul_f32_e32 v6, 0xbfb8aa3b, v5
	v_exp_f32_e32 v6, v6
	s_nop 0
	v_add_f32_e32 v6, 1.0, v6
	v_rcp_f32_e32 v6, v6
	s_nop 0
	v_mul_f32_e32 v5, v6, v5
	v_mul_f32_e32 v6, v13, v0
	v_mul_f32_e32 v5, v6, v5
	v_mov_b32_e32 v213, v1
	v_cvt_pk_fp8_f32 v213, v2, v3
	v_med3_f32 v2, v4, s93, v223
	v_med3_f32 v3, v5, s93, v223
	v_cvt_pk_fp8_f32 v213, v2, v3 op_sel:[0,0,1]
	s_waitcnt vmcnt(3)
	v_lshlrev_b32_e32 v2, 16, v66
	v_mul_f32_e32 v6, 0xbfb8aa3b, v2
	v_exp_f32_e32 v6, v6
	v_and_b32_e32 v3, 0xffff0000, v66
	v_lshlrev_b32_e32 v4, 16, v67
	v_and_b32_e32 v5, 0xffff0000, v67
	v_add_f32_e32 v6, 1.0, v6
	v_rcp_f32_e32 v6, v6
	s_nop 0
	v_mul_f32_e32 v2, v6, v2
	v_mul_f32_e32 v6, v14, v0
	v_mul_f32_e32 v2, v6, v2
	v_mul_f32_e32 v6, 0xbfb8aa3b, v3
	v_exp_f32_e32 v6, v6
	s_nop 0
	v_med3_f32 v2, v2, s93, v223
	v_add_f32_e32 v6, 1.0, v6
	v_rcp_f32_e32 v6, v6
	s_nop 0
	v_mul_f32_e32 v3, v6, v3
	v_mul_f32_e32 v6, v15, v0
	v_mul_f32_e32 v3, v6, v3
	v_mul_f32_e32 v6, 0xbfb8aa3b, v4
	v_exp_f32_e32 v6, v6
	s_nop 0
	v_med3_f32 v3, v3, s93, v223
	v_add_f32_e32 v6, 1.0, v6
	v_rcp_f32_e32 v6, v6
	s_nop 0
	v_mul_f32_e32 v4, v6, v4
	v_mul_f32_e32 v6, v16, v0
	v_mul_f32_e32 v4, v6, v4
	v_mul_f32_e32 v6, 0xbfb8aa3b, v5
	v_exp_f32_e32 v6, v6
	v_mul_f32_e32 v0, v17, v0
	v_add_f32_e32 v6, 1.0, v6
	v_rcp_f32_e32 v6, v6
	s_nop 0
	v_mul_f32_e32 v5, v6, v5
	v_mul_f32_e32 v0, v0, v5
	v_mov_b32_e32 v215, v1
	v_cvt_pk_fp8_f32 v215, v2, v3
	v_med3_f32 v2, v4, s93, v223
	v_med3_f32 v0, v0, s93, v223
	v_cvt_pk_fp8_f32 v215, v2, v0 op_sel:[0,0,1]
	s_nop 1
	v_permlane32_swap_b32_e32 v212, v213
	v_permlane32_swap_b32_e32 v214, v215
	global_store_dwordx4 v[216:217], v[212:215], off offset:2144
	s_branch .LBB0_1239

; template <int DQK, int W1, int DV, int VW, int MODE> ...
;     ...
;         f32x16 e0 = s[0], e1 = s[1];
;         if (MODE != 0) { const float nm = -m; e0 = e0 + nm; e1 = e1 + nm; }
; #pragma unroll
;         for (int i = 0; i < 16; ++i) { e0[i] = __builtin_amdgcn_exp2f(e0[i]); e1[i] = __builtin_amdgcn_exp2f(e1[i]); }
;         s[0] = e0; s[1] = e1;
;         const f32x16 sm = e0 + e1;
;         typedef __attribute__((ext_vector_type(8))) float f32x8;
;         const f32x8 h8 = sm.lo + sm.hi;
;         const f32x4 h4 = h8.lo + h8.hi;
;         const f32x2 h2 = h4.lo + h4.hi;
;         l += h2[0] + h2[1];
;       }
;       bf16x8 pb[2][2];
; #pragma unroll
;       for (int n = 0; n < 2; ++n)
; #pragma unroll
;         for (int s2 = 0; s2 < 2; ++s2) {
;           u32x4 pw = {pk2(s[n][8 * s2 + 0], s[n][8 * s2 + 1]), pk2(s[n][8 * s2 + 2], s[n][8 * s2 + 3]),
;                       pk2(s[n][8 * s2 + 4], s[n][8 * s2 + 5]), pk2(s[n][8 * s2 + 6], s[n][8 * s2 + 7])};
;           pb[n][s2] = __builtin_bit_cast(bf16x8, pw);
;         }
;       pv_block<0>(o[0], bufa + vlane, pb);
;       if constexpr (NCB > 1) pv_block<1>(o[1], bufa + vlane, pb);
;       if constexpr (NCB > 2) pv_block<2>(o[2], bufa + vlane, pb);
;       if constexpr (NCB > 3) pv_block<3>(o[3], bufa + vlane, pb);
.LBB0_1319:
	v_mov_b32_e32 v105, v104
	v_mov_b32_e32 v68, v104
	v_mov_b32_e32 v69, v104
	v_mov_b32_e32 v70, v104
	v_mov_b32_e32 v71, v104
	v_mov_b32_e32 v72, v104
	v_mov_b32_e32 v73, v104
	v_mov_b32_e32 v74, v104
	v_mov_b32_e32 v75, v104
	v_mov_b32_e32 v76, v104
	v_mov_b32_e32 v77, v104
	v_mov_b32_e32 v78, v104
	v_mov_b32_e32 v79, v104
	v_mov_b32_e32 v80, v104
	v_mov_b32_e32 v81, v104
	v_pk_add_f32 v[64:65], v[64:65], v[80:81]
	v_pk_add_f32 v[62:63], v[62:63], v[78:79]
	v_pk_add_f32 v[60:61], v[60:61], v[76:77]
	v_pk_add_f32 v[58:59], v[58:59], v[74:75]
	v_pk_add_f32 v[56:57], v[56:57], v[72:73]
	v_pk_add_f32 v[54:55], v[54:55], v[70:71]
	v_pk_add_f32 v[52:53], v[52:53], v[68:69]
	v_pk_add_f32 v[50:51], v[50:51], v[104:105]
	v_pk_add_f32 v[48:49], v[48:49], v[80:81]
	v_pk_add_f32 v[46:47], v[46:47], v[78:79]
	v_pk_add_f32 v[44:45], v[44:45], v[76:77]
	v_pk_add_f32 v[42:43], v[42:43], v[74:75]
	v_pk_add_f32 v[66:67], v[66:67], v[72:73]
	v_pk_add_f32 v[38:39], v[38:39], v[70:71]
	v_pk_add_f32 v[36:37], v[36:37], v[68:69]
	v_pk_add_f32 v[34:35], v[34:35], v[104:105]
	v_exp_f32_e32 v50, v50
	v_exp_f32_e32 v68, v34
	v_exp_f32_e32 v51, v51
	v_exp_f32_e32 v69, v35
	v_exp_f32_e32 v52, v52
	v_exp_f32_e32 v70, v36
	v_exp_f32_e32 v53, v53
	v_exp_f32_e32 v71, v37
	v_exp_f32_e32 v36, v54
	v_exp_f32_e32 v38, v38
	v_exp_f32_e32 v37, v55
	v_exp_f32_e32 v39, v39
	v_exp_f32_e32 v54, v56
	v_exp_f32_e32 v56, v66
	v_exp_f32_e32 v55, v57
	v_exp_f32_e32 v57, v67
	v_exp_f32_e32 v58, v58
	v_exp_f32_e32 v66, v42
	v_exp_f32_e32 v59, v59
	v_exp_f32_e32 v67, v43
	v_exp_f32_e32 v60, v60
	v_exp_f32_e32 v72, v44
	v_exp_f32_e32 v61, v61
	v_exp_f32_e32 v73, v45
	v_exp_f32_e32 v44, v62
	v_exp_f32_e32 v62, v46
	v_exp_f32_e32 v45, v63
	v_exp_f32_e32 v63, v47
	v_exp_f32_e32 v46, v64
	v_exp_f32_e32 v64, v48
	v_exp_f32_e32 v47, v65
	v_exp_f32_e32 v65, v49
	v_mov_b64_e32 v[40:41], s[82:83]
	v_mad_u64_u32 v[40:41], s[0:1], v86, s34, v[40:41]
	v_mad_i32_i24 v41, v87, s34, v41
	v_pk_add_f32 v[34:35], v[60:61], v[72:73]
	v_pk_add_f32 v[42:43], v[52:53], v[70:71]
	v_pk_add_f32 v[48:49], v[46:47], v[64:65]
	v_pk_add_f32 v[74:75], v[54:55], v[56:57]
	v_pk_add_f32 v[76:77], v[50:51], v[68:69]
	v_pk_add_f32 v[78:79], v[58:59], v[66:67]
	v_pk_add_f32 v[80:81], v[44:45], v[62:63]
	v_pk_add_f32 v[86:87], v[36:37], v[38:39]
	v_pk_add_f32 v[76:77], v[76:77], v[78:79]
	v_pk_add_f32 v[80:81], v[86:87], v[80:81]
	v_pk_add_f32 v[48:49], v[74:75], v[48:49]
	v_pk_add_f32 v[34:35], v[42:43], v[34:35]
	v_pk_add_f32 v[42:43], v[76:77], v[80:81]
	v_pk_add_f32 v[34:35], v[34:35], v[48:49]
	v_cvt_pk_bf16_f32 v36, v36, v37
	v_pk_add_f32 v[34:35], v[42:43], v[34:35]
	v_cvt_pk_bf16_f32 v37, v54, v55
	v_add_f32_e32 v74, v34, v35
	v_cvt_pk_bf16_f32 v34, v50, v51
	v_cvt_pk_bf16_f32 v35, v52, v53
	v_cvt_pk_bf16_f32 v42, v58, v59
	v_cvt_pk_bf16_f32 v43, v60, v61
	v_cvt_pk_bf16_f32 v44, v44, v45
	v_cvt_pk_bf16_f32 v45, v46, v47
	v_cvt_pk_bf16_f32 v46, v68, v69
	v_cvt_pk_bf16_f32 v49, v56, v57
	v_cvt_pk_bf16_f32 v50, v66, v67
	v_cvt_pk_bf16_f32 v52, v62, v63
	v_cvt_pk_bf16_f32 v53, v64, v65
	ds_read_b64_tr_b16 v[66:67], v101 offset:0
	ds_read_b64_tr_b16 v[68:69], v101 offset:0x200
	ds_read_b64_tr_b16 v[62:63], v101 offset:0x400
	ds_read_b64_tr_b16 v[64:65], v101 offset:0x600
	ds_read_b64_tr_b16 v[58:59], v101 offset:0x800
	ds_read_b64_tr_b16 v[60:61], v101 offset:0xa00
	ds_read_b64_tr_b16 v[54:55], v101 offset:0xc00
	ds_read_b64_tr_b16 v[56:57], v101 offset:0xe00
	s_waitcnt lgkmcnt(0)
	v_cvt_pk_bf16_f32 v47, v70, v71
	v_mfma_f32_32x32x16_bf16 v[18:33], v[66:69], v[34:37], v[18:33]
	v_cvt_pk_bf16_f32 v48, v38, v39
	v_cvt_pk_bf16_f32 v51, v72, v73
	v_add_f32_e32 v38, v106, v74
	s_mov_b64 s[0:1], 0x1c00
	v_lshl_add_u64 v[40:41], v[40:41], 0, s[18:19]
	v_mov_b32_e32 v83, v1
	v_mfma_f32_32x32x16_bf16 v[18:33], v[62:65], v[42:45], v[18:33]
	v_mfma_f32_32x32x16_bf16 v[18:33], v[58:61], v[46:49], v[18:33]
	v_mfma_f32_32x32x16_bf16 v[18:33], v[54:57], v[50:53], v[18:33]
	ds_read_b64_tr_b16 v[66:67], v101 offset:0x1000
	ds_read_b64_tr_b16 v[68:69], v101 offset:0x1200
	ds_read_b64_tr_b16 v[62:63], v101 offset:0x1400
	ds_read_b64_tr_b16 v[64:65], v101 offset:0x1600
	ds_read_b64_tr_b16 v[58:59], v101 offset:0x1800
	ds_read_b64_tr_b16 v[60:61], v101 offset:0x1a00
	ds_read_b64_tr_b16 v[54:55], v101 offset:0x1c00
	ds_read_b64_tr_b16 v[56:57], v101 offset:0x1e00
	s_waitcnt lgkmcnt(0)
	s_waitcnt vmcnt(0)
	s_barrier
; DI float bf2f(unsigned b) { return __uint_as_float(b << 16); }
; template <int DQK, int W1, int DV, int VW, int MODE> ...
;     ...
;       pv_block<0>(o[0], bufa + vlane, pb);
;       if constexpr (NCB > 1) pv_block<1>(o[1], bufa + vlane, pb);
;       if constexpr (NCB > 2) pv_block<2>(o[2], bufa + vlane, pb);
;       if constexpr (NCB > 3) pv_block<3>(o[3], bufa + vlane, pb);
;     }
;     asm volatile("s_waitcnt vmcnt(0)" ::: "memory");
;     __syncthreads();
;   }
;   const float inv = __builtin_amdgcn_rcpf(xhalf_sum(l));
;   u32x2 ggv[NCB * 4];
; #pragma unroll
;   for (int cb = 0; cb < NCB; ++cb)
; #pragma unroll
;     for (int g = 0; g < 4; ++g) ggv[cb * 4 + g] = *(const u32x2*)(grow + 32 * cb + 8 * g + 4 * hi);
;   __builtin_amdgcn_sched_barrier(0);
; #pragma unroll
;   for (int cb = 0; cb < NCB; ++cb)
; #pragma unroll
;     for (int g = 0; g < 4; ++g) {
;       const int dv = 32 * cb + 8 * g + 4 * hi;
;       const u32x2 gg = ggv[cb * 4 + g];
;       float gv[4] = {bf2f(gg[0] & 0xffffu), bf2f(gg[0] >> 16), bf2f(gg[1] & 0xffffu), bf2f(gg[1] >> 16)};
;       float ov[4];
; #pragma unroll
;       for (int j = 0; j < 4; ++j) {
;         const float sg = gv[j] * __builtin_amdgcn_rcpf(1.f + __builtin_amdgcn_exp2f(-LOG2E * gv[j]));
;         ov[j] = o[cb][4 * g + j] * inv * sg;
;       }
;       *(unsigned*)((unsigned char*)yrow + dv) = pk4_fp8(ov[0] * Y_SCALE, ov[1] * Y_SCALE, ov[2] * Y_SCALE, ov[3] * Y_SCALE);
;       __builtin_amdgcn_sched_barrier(0);
;     }
	v_mfma_f32_32x32x16_bf16 v[2:17], v[66:69], v[34:37], v[2:17]
	v_mov_b32_e32 v34, v38
	s_nop 1
	v_permlane32_swap_b32_e32 v38, v34
	v_mov_b32_e32 v35, v1
	v_mfma_f32_32x32x16_bf16 v[2:17], v[62:65], v[42:45], v[2:17]
	v_mfma_f32_32x32x16_bf16 v[2:17], v[58:61], v[46:49], v[2:17]
	v_mfma_f32_32x32x16_bf16 v[2:17], v[54:57], v[50:53], v[2:17]
	v_add_f32_e32 v54, v38, v34
	v_lshlrev_b32_e32 v34, 1, v82
	v_lshl_add_u64 v[34:35], v[84:85], 0, v[34:35]
	v_lshl_add_u64 v[50:51], v[34:35], 0, s[0:1]
	s_movk_i32 s0, 0x1000
	v_add_co_u32_e32 v34, vcc, s0, v34
	s_nop 1
	v_addc_co_u32_e32 v35, vcc, 0, v35, vcc
	v_bfe_i32 v211, v179, 5, 1
	v_mul_i32_i24_e32 v210, 24, v211
	v_lshl_add_u64 v[208:209], v[50:51], 0, v[210:211]
	global_load_dwordx2 v[52:53], v[34:35], off offset:3072
	global_load_dwordx4 v[46:49], v[208:209], off offset:32
	global_load_dwordx4 v[42:45], v[208:209], off offset:64
	global_load_dwordx4 v[36:39], v[208:209], off offset:96
	global_load_dwordx2 v[34:35], v[50:51], off offset:112
	v_rcp_f32_e32 v50, v54
	s_waitcnt vmcnt(4)
	v_lshlrev_b32_e32 v51, 16, v52
	v_mul_f32_e32 v55, 0xbfb8aa3b, v51
	v_exp_f32_e32 v55, v55
	v_and_b32_e32 v52, 0xffff0000, v52
	v_mul_f32_e32 v50, 0x41800000, v50
	v_mul_f32_e32 v18, v18, v50
	v_lshlrev_b32_e32 v54, 16, v53
	v_add_f32_e32 v55, 1.0, v55
	v_rcp_f32_e32 v55, v55
	v_mul_f32_e32 v19, v19, v50
	v_and_b32_e32 v53, 0xffff0000, v53
	v_mul_f32_e32 v20, v20, v50
	v_mul_f32_e32 v51, v55, v51
	v_mul_f32_e32 v18, v18, v51
	v_mul_f32_e32 v51, 0xbfb8aa3b, v52
	v_exp_f32_e32 v51, v51
	v_mul_f32_e32 v21, v21, v50
	v_med3_f32 v18, v18, s93, v223
	v_add_f32_e32 v51, 1.0, v51
	v_rcp_f32_e32 v51, v51
	s_nop 0
	v_mul_f32_e32 v51, v51, v52
	v_mul_f32_e32 v19, v19, v51
	v_mul_f32_e32 v51, 0xbfb8aa3b, v54
	v_exp_f32_e32 v51, v51
	s_nop 0
	v_med3_f32 v19, v19, s93, v223
	v_add_f32_e32 v51, 1.0, v51
	v_rcp_f32_e32 v51, v51
	s_nop 0
	v_mul_f32_e32 v51, v51, v54
	v_mul_f32_e32 v20, v20, v51
	v_mul_f32_e32 v51, 0xbfb8aa3b, v53
	v_exp_f32_e32 v51, v51
	s_nop 0
	v_add_f32_e32 v51, 1.0, v51
	v_rcp_f32_e32 v51, v51
	s_nop 0
	v_mul_f32_e32 v51, v51, v53
	v_mul_f32_e32 v21, v21, v51
	v_mov_b32_e32 v212, v1
	v_cvt_pk_fp8_f32 v212, v18, v19
	v_med3_f32 v18, v20, s93, v223
	v_med3_f32 v19, v21, s93, v223
	v_cvt_pk_fp8_f32 v212, v18, v19 op_sel:[0,0,1]
	v_lshl_add_u64 v[18:19], v[40:41], 0, v[82:83]
	s_waitcnt vmcnt(3)
	v_permlane32_swap_b32_e32 v46, v48
	v_permlane32_swap_b32_e32 v47, v49
	v_lshlrev_b32_e32 v20, 16, v48
	v_and_b32_e32 v21, 0xffff0000, v48
	v_mul_f32_e32 v48, 0xbfb8aa3b, v20
	v_exp_f32_e32 v48, v48
	v_mul_f32_e32 v22, v22, v50
	v_lshlrev_b32_e32 v40, 16, v49
	v_and_b32_e32 v41, 0xffff0000, v49
	v_add_f32_e32 v48, 1.0, v48
	v_rcp_f32_e32 v48, v48
	s_nop 0
	v_mul_f32_e32 v20, v48, v20
	v_mul_f32_e32 v20, v22, v20
	v_mul_f32_e32 v22, 0xbfb8aa3b, v21
	v_exp_f32_e32 v22, v22
	s_nop 0
	v_med3_f32 v20, v20, s93, v223
	v_add_f32_e32 v22, 1.0, v22
	v_rcp_f32_e32 v22, v22
	s_nop 0
	v_mul_f32_e32 v21, v22, v21
	v_mul_f32_e32 v22, v23, v50
	v_mul_f32_e32 v21, v22, v21
	v_mul_f32_e32 v22, 0xbfb8aa3b, v40
	v_exp_f32_e32 v22, v22
	v_mul_f32_e32 v23, v24, v50
	v_mul_f32_e32 v24, v25, v50
	v_add_f32_e32 v22, 1.0, v22
	v_rcp_f32_e32 v22, v22
	v_med3_f32 v21, v21, s93, v223
	v_mul_f32_e32 v22, v22, v40
	v_mul_f32_e32 v22, v23, v22
	v_mul_f32_e32 v23, 0xbfb8aa3b, v41
	v_exp_f32_e32 v23, v23
	s_nop 0
	v_add_f32_e32 v23, 1.0, v23
	v_rcp_f32_e32 v23, v23
	s_nop 0
	v_mul_f32_e32 v23, v23, v41
	v_mul_f32_e32 v23, v24, v23
	v_mov_b32_e32 v214, v1
	v_cvt_pk_fp8_f32 v214, v20, v21
	v_med3_f32 v20, v22, s93, v223
	v_med3_f32 v21, v23, s93, v223
	v_cvt_pk_fp8_f32 v214, v20, v21 op_sel:[0,0,1]
	s_waitcnt vmcnt(3)
	v_lshlrev_b32_e32 v20, 16, v46
	v_mul_f32_e32 v24, 0xbfb8aa3b, v20
	v_exp_f32_e32 v24, v24
	v_and_b32_e32 v21, 0xffff0000, v46
	v_lshlrev_b32_e32 v22, 16, v47
	v_and_b32_e32 v23, 0xffff0000, v47
	v_add_f32_e32 v24, 1.0, v24
	v_rcp_f32_e32 v24, v24
	s_nop 0
	v_mul_f32_e32 v20, v24, v20
	v_mul_f32_e32 v24, v26, v50
	v_mul_f32_e32 v20, v24, v20
	v_mul_f32_e32 v24, 0xbfb8aa3b, v21
	v_exp_f32_e32 v24, v24
	s_nop 0
	v_med3_f32 v20, v20, s93, v223
	v_add_f32_e32 v24, 1.0, v24
	v_rcp_f32_e32 v24, v24
	s_nop 0
	v_mul_f32_e32 v21, v24, v21
	v_mul_f32_e32 v24, v27, v50
	v_mul_f32_e32 v21, v24, v21
	v_mul_f32_e32 v24, 0xbfb8aa3b, v22
	v_exp_f32_e32 v24, v24
	s_nop 0
	v_med3_f32 v21, v21, s93, v223
	v_add_f32_e32 v24, 1.0, v24
	v_rcp_f32_e32 v24, v24
	s_nop 0
	v_mul_f32_e32 v22, v24, v22
	v_mul_f32_e32 v24, v28, v50
	v_mul_f32_e32 v22, v24, v22
	v_mul_f32_e32 v24, 0xbfb8aa3b, v23
	v_exp_f32_e32 v24, v24
	s_nop 0
	v_add_f32_e32 v24, 1.0, v24
	v_rcp_f32_e32 v24, v24
	s_nop 0
	v_mul_f32_e32 v23, v24, v23
	v_mul_f32_e32 v24, v29, v50
	v_mul_f32_e32 v23, v24, v23
	v_mov_b32_e32 v213, v1
	v_cvt_pk_fp8_f32 v213, v20, v21
	v_med3_f32 v20, v22, s93, v223
	v_med3_f32 v21, v23, s93, v223
	v_cvt_pk_fp8_f32 v213, v20, v21 op_sel:[0,0,1]
	s_waitcnt vmcnt(2)
; DI float bf2f(unsigned b) { return __uint_as_float(b << 16); }
; template <int DQK, int W1, int DV, int VW, int MODE> ...
;     ...
; #pragma unroll
;   for (int cb = 0; cb < NCB; ++cb)
; #pragma unroll
;     for (int g = 0; g < 4; ++g) {
;       const int dv = 32 * cb + 8 * g + 4 * hi;
;       const u32x2 gg = ggv[cb * 4 + g];
;       float gv[4] = {bf2f(gg[0] & 0xffffu), bf2f(gg[0] >> 16), bf2f(gg[1] & 0xffffu), bf2f(gg[1] >> 16)};
;       float ov[4];
; #pragma unroll
;       for (int j = 0; j < 4; ++j) {
;         const float sg = gv[j] * __builtin_amdgcn_rcpf(1.f + __builtin_amdgcn_exp2f(-LOG2E * gv[j]));
;         ov[j] = o[cb][4 * g + j] * inv * sg;
;       }
;       *(unsigned*)((unsigned char*)yrow + dv) = pk4_fp8(ov[0] * Y_SCALE, ov[1] * Y_SCALE, ov[2] * Y_SCALE, ov[3] * Y_SCALE);
;       __builtin_amdgcn_sched_barrier(0);
;     }
	v_permlane32_swap_b32_e32 v42, v44
	v_permlane32_swap_b32_e32 v43, v45
	v_lshlrev_b32_e32 v20, 16, v44
	v_mul_f32_e32 v24, 0xbfb8aa3b, v20
	v_exp_f32_e32 v24, v24
	v_and_b32_e32 v21, 0xffff0000, v44
	v_lshlrev_b32_e32 v22, 16, v45
	v_and_b32_e32 v23, 0xffff0000, v45
	v_add_f32_e32 v24, 1.0, v24
	v_rcp_f32_e32 v24, v24
	s_nop 0
	v_mul_f32_e32 v20, v24, v20
	v_mul_f32_e32 v24, v30, v50
	v_mul_f32_e32 v20, v24, v20
	v_mul_f32_e32 v24, 0xbfb8aa3b, v21
	v_exp_f32_e32 v24, v24
	s_nop 0
	v_med3_f32 v20, v20, s93, v223
	v_add_f32_e32 v24, 1.0, v24
	v_rcp_f32_e32 v24, v24
	s_nop 0
	v_mul_f32_e32 v21, v24, v21
	v_mul_f32_e32 v24, v31, v50
	v_mul_f32_e32 v21, v24, v21
	v_mul_f32_e32 v24, 0xbfb8aa3b, v22
	v_exp_f32_e32 v24, v24
	s_nop 0
	v_med3_f32 v21, v21, s93, v223
	v_add_f32_e32 v24, 1.0, v24
	v_rcp_f32_e32 v24, v24
	s_nop 0
	v_mul_f32_e32 v22, v24, v22
	v_mul_f32_e32 v24, v32, v50
	v_mul_f32_e32 v22, v24, v22
	v_mul_f32_e32 v24, 0xbfb8aa3b, v23
	v_exp_f32_e32 v24, v24
	s_nop 0
	v_add_f32_e32 v24, 1.0, v24
	v_rcp_f32_e32 v24, v24
	s_nop 0
	v_mul_f32_e32 v23, v24, v23
	v_mul_f32_e32 v24, v33, v50
	v_mul_f32_e32 v23, v24, v23
	v_mov_b32_e32 v215, v1
	v_cvt_pk_fp8_f32 v215, v20, v21
	v_med3_f32 v20, v22, s93, v223
	v_med3_f32 v21, v23, s93, v223
	v_cvt_pk_fp8_f32 v215, v20, v21 op_sel:[0,0,1]
	v_and_b32_e32 v242, 32, v179
	v_lshrrev_b32_e32 v242, 3, v242
	v_lshl_add_u32 v242, v242, 1, v242
	v_mov_b32_e32 v243, 0
	v_lshl_add_u64 v[216:217], v[18:19], 0, v[242:243]
	s_nop 1
	v_permlane32_swap_b32_e32 v212, v213
	v_permlane32_swap_b32_e32 v214, v215
	global_store_dwordx4 v[216:217], v[212:215], off
	s_waitcnt vmcnt(3)
	v_lshlrev_b32_e32 v20, 16, v42
	v_mul_f32_e32 v24, 0xbfb8aa3b, v20
	v_exp_f32_e32 v24, v24
	v_and_b32_e32 v21, 0xffff0000, v42
	v_mul_f32_e32 v2, v2, v50
	v_lshlrev_b32_e32 v22, 16, v43
	v_add_f32_e32 v24, 1.0, v24
	v_rcp_f32_e32 v24, v24
	v_mul_f32_e32 v3, v3, v50
	v_and_b32_e32 v23, 0xffff0000, v43
	v_mul_f32_e32 v4, v4, v50
	v_mul_f32_e32 v20, v24, v20
	v_mul_f32_e32 v2, v2, v20
	v_mul_f32_e32 v20, 0xbfb8aa3b, v21
	v_exp_f32_e32 v20, v20
	v_mul_f32_e32 v5, v5, v50
	v_med3_f32 v2, v2, s93, v223
	v_add_f32_e32 v20, 1.0, v20
	v_rcp_f32_e32 v20, v20
	s_nop 0
	v_mul_f32_e32 v20, v20, v21
	v_mul_f32_e32 v3, v3, v20
	v_mul_f32_e32 v20, 0xbfb8aa3b, v22
	v_exp_f32_e32 v20, v20
	s_nop 0
	v_med3_f32 v3, v3, s93, v223
	v_add_f32_e32 v20, 1.0, v20
	v_rcp_f32_e32 v20, v20
	s_nop 0
	v_mul_f32_e32 v20, v20, v22
	v_mul_f32_e32 v4, v4, v20
	v_mul_f32_e32 v20, 0xbfb8aa3b, v23
	v_exp_f32_e32 v20, v20
	s_nop 0
	v_add_f32_e32 v20, 1.0, v20
	v_rcp_f32_e32 v20, v20
	s_nop 0
	v_mul_f32_e32 v20, v20, v23
	v_mul_f32_e32 v5, v5, v20
	v_mov_b32_e32 v212, v1
	v_cvt_pk_fp8_f32 v212, v2, v3
	v_med3_f32 v2, v4, s93, v223
	v_med3_f32 v3, v5, s93, v223
	v_cvt_pk_fp8_f32 v212, v2, v3 op_sel:[0,0,1]
	s_waitcnt vmcnt(2)
	v_permlane32_swap_b32_e32 v36, v38
	v_permlane32_swap_b32_e32 v37, v39
	v_lshlrev_b32_e32 v2, 16, v38
	v_mul_f32_e32 v20, 0xbfb8aa3b, v2
	v_exp_f32_e32 v20, v20
	v_and_b32_e32 v3, 0xffff0000, v38
	v_mul_f32_e32 v6, v6, v50
	v_lshlrev_b32_e32 v4, 16, v39
	v_add_f32_e32 v20, 1.0, v20
	v_rcp_f32_e32 v20, v20
	v_and_b32_e32 v5, 0xffff0000, v39
	v_mul_f32_e32 v2, v20, v2
	v_mul_f32_e32 v2, v6, v2
	v_mul_f32_e32 v6, 0xbfb8aa3b, v3
	v_exp_f32_e32 v6, v6
	s_nop 0
	v_med3_f32 v2, v2, s93, v223
	v_add_f32_e32 v6, 1.0, v6
	v_rcp_f32_e32 v6, v6
	s_nop 0
	v_mul_f32_e32 v3, v6, v3
	v_mul_f32_e32 v6, v7, v50
	v_mul_f32_e32 v3, v6, v3
	v_mul_f32_e32 v6, 0xbfb8aa3b, v4
	v_exp_f32_e32 v6, v6
	s_nop 0
	v_med3_f32 v3, v3, s93, v223
	v_add_f32_e32 v6, 1.0, v6
	v_rcp_f32_e32 v6, v6
	s_nop 0
	v_mul_f32_e32 v4, v6, v4
	v_mul_f32_e32 v6, v8, v50
	v_mul_f32_e32 v4, v6, v4
	v_mul_f32_e32 v6, 0xbfb8aa3b, v5
	v_exp_f32_e32 v6, v6
	s_nop 0
	v_add_f32_e32 v6, 1.0, v6
	v_rcp_f32_e32 v6, v6
	s_nop 0
	v_mul_f32_e32 v5, v6, v5
	v_mul_f32_e32 v6, v9, v50
	v_mul_f32_e32 v5, v6, v5
	v_mov_b32_e32 v214, v1
	v_cvt_pk_fp8_f32 v214, v2, v3
	v_med3_f32 v2, v4, s93, v223
	v_med3_f32 v3, v5, s93, v223
	v_cvt_pk_fp8_f32 v214, v2, v3 op_sel:[0,0,1]
	s_waitcnt vmcnt(2)
	v_lshlrev_b32_e32 v2, 16, v36
	v_mul_f32_e32 v6, 0xbfb8aa3b, v2
	v_exp_f32_e32 v6, v6
	v_and_b32_e32 v3, 0xffff0000, v36
	v_lshlrev_b32_e32 v4, 16, v37
	v_and_b32_e32 v5, 0xffff0000, v37
	v_add_f32_e32 v6, 1.0, v6
	v_rcp_f32_e32 v6, v6
	s_nop 0
	v_mul_f32_e32 v2, v6, v2
	v_mul_f32_e32 v6, v10, v50
	v_mul_f32_e32 v2, v6, v2
	v_mul_f32_e32 v6, 0xbfb8aa3b, v3
	v_exp_f32_e32 v6, v6
	s_nop 0
	v_med3_f32 v2, v2, s93, v223
	v_add_f32_e32 v6, 1.0, v6
	v_rcp_f32_e32 v6, v6
	s_nop 0
	v_mul_f32_e32 v3, v6, v3
	v_mul_f32_e32 v6, v11, v50
	v_mul_f32_e32 v3, v6, v3
	v_mul_f32_e32 v6, 0xbfb8aa3b, v4
	v_exp_f32_e32 v6, v6
	s_nop 0
	v_med3_f32 v3, v3, s93, v223
	v_add_f32_e32 v6, 1.0, v6
	v_rcp_f32_e32 v6, v6
	s_nop 0
	v_mul_f32_e32 v4, v6, v4
	v_mul_f32_e32 v6, v12, v50
	v_mul_f32_e32 v4, v6, v4
	v_mul_f32_e32 v6, 0xbfb8aa3b, v5
	v_exp_f32_e32 v6, v6
	s_nop 0
	v_add_f32_e32 v6, 1.0, v6
	v_rcp_f32_e32 v6, v6
	s_nop 0
	v_mul_f32_e32 v5, v6, v5
	v_mul_f32_e32 v6, v13, v50
	v_mul_f32_e32 v5, v6, v5
	v_mov_b32_e32 v213, v1
	v_cvt_pk_fp8_f32 v213, v2, v3
	v_med3_f32 v2, v4, s93, v223
	v_med3_f32 v3, v5, s93, v223
	v_cvt_pk_fp8_f32 v213, v2, v3 op_sel:[0,0,1]
	s_waitcnt vmcnt(1)
	v_lshlrev_b32_e32 v2, 16, v34
	v_mul_f32_e32 v6, 0xbfb8aa3b, v2
	v_exp_f32_e32 v6, v6
	v_and_b32_e32 v3, 0xffff0000, v34
	v_lshlrev_b32_e32 v4, 16, v35
	v_and_b32_e32 v5, 0xffff0000, v35
	v_add_f32_e32 v6, 1.0, v6
	v_rcp_f32_e32 v6, v6
	s_nop 0
	v_mul_f32_e32 v2, v6, v2
	v_mul_f32_e32 v6, v14, v50
	v_mul_f32_e32 v2, v6, v2
	v_mul_f32_e32 v6, 0xbfb8aa3b, v3
	v_exp_f32_e32 v6, v6
	s_nop 0
	v_med3_f32 v2, v2, s93, v223
	v_add_f32_e32 v6, 1.0, v6
	v_rcp_f32_e32 v6, v6
	s_nop 0
	v_mul_f32_e32 v3, v6, v3
	v_mul_f32_e32 v6, v15, v50
	v_mul_f32_e32 v3, v6, v3
	v_mul_f32_e32 v6, 0xbfb8aa3b, v4
	v_exp_f32_e32 v6, v6
	s_nop 0
	v_med3_f32 v3, v3, s93, v223
	v_add_f32_e32 v6, 1.0, v6
	v_rcp_f32_e32 v6, v6
	s_nop 0
	v_mul_f32_e32 v4, v6, v4
	v_mul_f32_e32 v6, v16, v50
	v_mul_f32_e32 v4, v6, v4
	v_mul_f32_e32 v6, 0xbfb8aa3b, v5
	v_exp_f32_e32 v6, v6
	s_nop 0
	v_add_f32_e32 v6, 1.0, v6
	v_rcp_f32_e32 v6, v6
	s_nop 0
	v_mul_f32_e32 v5, v6, v5
	v_mul_f32_e32 v6, v17, v50
	v_mul_f32_e32 v5, v6, v5
	v_mov_b32_e32 v215, v1
	v_cvt_pk_fp8_f32 v215, v2, v3
	v_med3_f32 v2, v4, s93, v223
	v_med3_f32 v3, v5, s93, v223
	v_cvt_pk_fp8_f32 v215, v2, v3 op_sel:[0,0,1]
	s_nop 1
	v_permlane32_swap_b32_e32 v212, v213
	v_permlane32_swap_b32_e32 v214, v215
	global_store_dwordx4 v[216:217], v[212:215], off offset:32
	s_mov_b64 s[0:1], 0

; DI float bf2f(unsigned b) { return __uint_as_float(b << 16); }
; template <int DQK, int W1, int DV, int VW, int MODE> ...
;     ...
;   const float inv = __builtin_amdgcn_rcpf(xhalf_sum(l));
;   u32x2 ggv[NCB * 4];
; #pragma unroll
;   for (int cb = 0; cb < NCB; ++cb)
; #pragma unroll
;     for (int g = 0; g < 4; ++g) ggv[cb * 4 + g] = *(const u32x2*)(grow + 32 * cb + 8 * g + 4 * hi);
;   __builtin_amdgcn_sched_barrier(0);
; #pragma unroll
;   for (int cb = 0; cb < NCB; ++cb)
; #pragma unroll
;     for (int g = 0; g < 4; ++g) {
;       const int dv = 32 * cb + 8 * g + 4 * hi;
;       const u32x2 gg = ggv[cb * 4 + g];
;       float gv[4] = {bf2f(gg[0] & 0xffffu), bf2f(gg[0] >> 16), bf2f(gg[1] & 0xffffu), bf2f(gg[1] >> 16)};
;       float ov[4];
; #pragma unroll
;       for (int j = 0; j < 4; ++j) {
;         const float sg = gv[j] * __builtin_amdgcn_rcpf(1.f + __builtin_amdgcn_exp2f(-LOG2E * gv[j]));
;         ov[j] = o[cb][4 * g + j] * inv * sg;
;       }
;       *(unsigned*)((unsigned char*)yrow + dv) = pk4_fp8(ov[0] * Y_SCALE, ov[1] * Y_SCALE, ov[2] * Y_SCALE, ov[3] * Y_SCALE);
;       __builtin_amdgcn_sched_barrier(0);
;     }
.LBB0_1348:
	v_mov_b64_e32 v[34:35], s[82:83]
	v_mov_b32_e32 v0, v119
	v_mad_u64_u32 v[34:35], s[0:1], v86, s34, v[34:35]
	s_nop 0
	v_permlane32_swap_b32_e32 v119, v0
	v_mad_i32_i24 v35, v87, s34, v35
	v_add_f32_e32 v54, v119, v0
	v_lshlrev_b32_e32 v0, 1, v82
	v_lshl_add_u64 v[46:47], v[34:35], 0, s[10:11]
	v_lshl_add_u64 v[34:35], v[84:85], 0, v[0:1]
	s_mov_b64 s[0:1], 0x24a0
	v_lshl_add_u64 v[48:49], v[34:35], 0, s[0:1]
	s_movk_i32 s0, 0x2000
	v_add_co_u32_e32 v34, vcc, s0, v34
	v_mov_b32_e32 v83, v1
	s_nop 0
	v_addc_co_u32_e32 v35, vcc, 0, v35, vcc
	v_bfe_i32 v211, v179, 5, 1
	v_mul_i32_i24_e32 v210, 24, v211
	v_lshl_add_u64 v[208:209], v[48:49], 0, v[210:211]
	global_load_dwordx2 v[50:51], v[34:35], off offset:1184
	global_load_dwordx2 v[52:53], v[48:49], off offset:16
	global_load_dwordx4 v[42:45], v[208:209], off offset:48
	global_load_dwordx4 v[38:41], v[208:209], off offset:80
	global_load_dwordx4 v[34:37], v[208:209], off offset:112
	v_rcp_f32_e32 v0, v54
	s_waitcnt vmcnt(4)
	v_lshlrev_b32_e32 v48, 16, v50
	v_mul_f32_e32 v54, 0xbfb8aa3b, v48
	v_exp_f32_e32 v54, v54
	v_and_b32_e32 v49, 0xffff0000, v50
	v_mul_f32_e32 v0, 0x41800000, v0
	v_mul_f32_e32 v18, v18, v0
	v_lshlrev_b32_e32 v50, 16, v51
	v_add_f32_e32 v54, 1.0, v54
	v_rcp_f32_e32 v54, v54
	v_mul_f32_e32 v19, v19, v0
	v_and_b32_e32 v51, 0xffff0000, v51
	v_mul_f32_e32 v20, v20, v0
	v_mul_f32_e32 v48, v54, v48
	v_mul_f32_e32 v18, v18, v48
	v_mul_f32_e32 v48, 0xbfb8aa3b, v49
	v_exp_f32_e32 v48, v48
	v_mul_f32_e32 v21, v21, v0
	v_med3_f32 v18, v18, s93, v223
	v_add_f32_e32 v48, 1.0, v48
	v_rcp_f32_e32 v48, v48
	s_nop 0
	v_mul_f32_e32 v48, v48, v49
	v_mul_f32_e32 v19, v19, v48
	v_mul_f32_e32 v48, 0xbfb8aa3b, v50
	v_exp_f32_e32 v48, v48
	s_nop 0
	v_med3_f32 v19, v19, s93, v223
	v_add_f32_e32 v48, 1.0, v48
	v_rcp_f32_e32 v48, v48
	s_nop 0
	v_mul_f32_e32 v48, v48, v50
	v_mul_f32_e32 v20, v20, v48
	v_mul_f32_e32 v48, 0xbfb8aa3b, v51
	v_exp_f32_e32 v48, v48
	s_nop 0
	v_add_f32_e32 v48, 1.0, v48
	v_rcp_f32_e32 v48, v48
	s_nop 0
	v_mul_f32_e32 v48, v48, v51
	v_mul_f32_e32 v21, v21, v48
	v_mov_b32_e32 v212, v1
	v_cvt_pk_fp8_f32 v212, v18, v19
	v_med3_f32 v18, v20, s93, v223
	v_med3_f32 v19, v21, s93, v223
	v_cvt_pk_fp8_f32 v212, v18, v19 op_sel:[0,0,1]
	v_lshl_add_u64 v[18:19], v[46:47], 0, v[82:83]
	s_waitcnt vmcnt(3)
	v_lshlrev_b32_e32 v20, 16, v52
	v_mul_f32_e32 v48, 0xbfb8aa3b, v20
	v_exp_f32_e32 v48, v48
	v_and_b32_e32 v21, 0xffff0000, v52
	v_mul_f32_e32 v22, v22, v0
	v_lshlrev_b32_e32 v46, 16, v53
	v_add_f32_e32 v48, 1.0, v48
	v_rcp_f32_e32 v48, v48
	v_and_b32_e32 v47, 0xffff0000, v53
	v_mul_f32_e32 v20, v48, v20
	v_mul_f32_e32 v20, v22, v20
	v_mul_f32_e32 v22, 0xbfb8aa3b, v21
	v_exp_f32_e32 v22, v22
	s_nop 0
	v_med3_f32 v20, v20, s93, v223
	v_add_f32_e32 v22, 1.0, v22
	v_rcp_f32_e32 v22, v22
	s_nop 0
	v_mul_f32_e32 v21, v22, v21
	v_mul_f32_e32 v22, v23, v0
	v_mul_f32_e32 v21, v22, v21
	v_mul_f32_e32 v22, 0xbfb8aa3b, v46
	v_exp_f32_e32 v22, v22
	v_mul_f32_e32 v23, v24, v0
	v_mul_f32_e32 v24, v25, v0
	v_add_f32_e32 v22, 1.0, v22
	v_rcp_f32_e32 v22, v22
	v_med3_f32 v21, v21, s93, v223
	v_mul_f32_e32 v22, v22, v46
	v_mul_f32_e32 v22, v23, v22
	v_mul_f32_e32 v23, 0xbfb8aa3b, v47
	v_exp_f32_e32 v23, v23
	s_nop 0
	v_add_f32_e32 v23, 1.0, v23
	v_rcp_f32_e32 v23, v23
	s_nop 0
	v_mul_f32_e32 v23, v23, v47
	v_mul_f32_e32 v23, v24, v23
	v_mov_b32_e32 v214, v1
	v_cvt_pk_fp8_f32 v214, v20, v21
	v_med3_f32 v20, v22, s93, v223
	v_med3_f32 v21, v23, s93, v223
	v_cvt_pk_fp8_f32 v214, v20, v21 op_sel:[0,0,1]
	s_waitcnt vmcnt(2)
	v_permlane32_swap_b32_e32 v42, v44
	v_permlane32_swap_b32_e32 v43, v45
	v_lshlrev_b32_e32 v20, 16, v44
	v_mul_f32_e32 v24, 0xbfb8aa3b, v20
	v_exp_f32_e32 v24, v24
	v_and_b32_e32 v21, 0xffff0000, v44
	v_lshlrev_b32_e32 v22, 16, v45
	v_and_b32_e32 v23, 0xffff0000, v45
	v_add_f32_e32 v24, 1.0, v24
	v_rcp_f32_e32 v24, v24
	s_nop 0
	v_mul_f32_e32 v20, v24, v20
	v_mul_f32_e32 v24, v26, v0
	v_mul_f32_e32 v20, v24, v20
	v_mul_f32_e32 v24, 0xbfb8aa3b, v21
	v_exp_f32_e32 v24, v24
	s_nop 0
	v_med3_f32 v20, v20, s93, v223
	v_add_f32_e32 v24, 1.0, v24
	v_rcp_f32_e32 v24, v24
	s_nop 0
	v_mul_f32_e32 v21, v24, v21
	v_mul_f32_e32 v24, v27, v0
	v_mul_f32_e32 v21, v24, v21
	v_mul_f32_e32 v24, 0xbfb8aa3b, v22
	v_exp_f32_e32 v24, v24
	s_nop 0
	v_med3_f32 v21, v21, s93, v223
	v_add_f32_e32 v24, 1.0, v24
	v_rcp_f32_e32 v24, v24
	s_nop 0
	v_mul_f32_e32 v22, v24, v22
	v_mul_f32_e32 v24, v28, v0
	v_mul_f32_e32 v22, v24, v22
	v_mul_f32_e32 v24, 0xbfb8aa3b, v23
	v_exp_f32_e32 v24, v24
	s_nop 0
	v_add_f32_e32 v24, 1.0, v24
	v_rcp_f32_e32 v24, v24
	s_nop 0
	v_mul_f32_e32 v23, v24, v23
	v_mul_f32_e32 v24, v29, v0
	v_mul_f32_e32 v23, v24, v23
	v_mov_b32_e32 v213, v1
	v_cvt_pk_fp8_f32 v213, v20, v21
	v_med3_f32 v20, v22, s93, v223
	v_med3_f32 v21, v23, s93, v223
	v_cvt_pk_fp8_f32 v213, v20, v21 op_sel:[0,0,1]
	s_waitcnt vmcnt(2)
	v_lshlrev_b32_e32 v20, 16, v42
	v_mul_f32_e32 v24, 0xbfb8aa3b, v20
	v_exp_f32_e32 v24, v24
	v_and_b32_e32 v21, 0xffff0000, v42
	v_lshlrev_b32_e32 v22, 16, v43
	v_and_b32_e32 v23, 0xffff0000, v43
	v_add_f32_e32 v24, 1.0, v24
	v_rcp_f32_e32 v24, v24
	s_nop 0
	v_mul_f32_e32 v20, v24, v20
	v_mul_f32_e32 v24, v30, v0
	v_mul_f32_e32 v20, v24, v20
	v_mul_f32_e32 v24, 0xbfb8aa3b, v21
	v_exp_f32_e32 v24, v24
	s_nop 0
	v_med3_f32 v20, v20, s93, v223
	v_add_f32_e32 v24, 1.0, v24
	v_rcp_f32_e32 v24, v24
	s_nop 0
	v_mul_f32_e32 v21, v24, v21
	v_mul_f32_e32 v24, v31, v0
	v_mul_f32_e32 v21, v24, v21
	v_mul_f32_e32 v24, 0xbfb8aa3b, v22
	v_exp_f32_e32 v24, v24
	s_nop 0
	v_med3_f32 v21, v21, s93, v223
	v_add_f32_e32 v24, 1.0, v24
	v_rcp_f32_e32 v24, v24
	s_nop 0
	v_mul_f32_e32 v22, v24, v22
	v_mul_f32_e32 v24, v32, v0
	v_mul_f32_e32 v22, v24, v22
	v_mul_f32_e32 v24, 0xbfb8aa3b, v23
	v_exp_f32_e32 v24, v24
	s_nop 0
	v_add_f32_e32 v24, 1.0, v24
	v_rcp_f32_e32 v24, v24
	s_nop 0
	v_mul_f32_e32 v23, v24, v23
	v_mul_f32_e32 v24, v33, v0
	v_mul_f32_e32 v23, v24, v23
	v_mov_b32_e32 v215, v1
	v_cvt_pk_fp8_f32 v215, v20, v21
	v_med3_f32 v20, v22, s93, v223
	v_med3_f32 v21, v23, s93, v223
	v_cvt_pk_fp8_f32 v215, v20, v21 op_sel:[0,0,1]
	v_and_b32_e32 v242, 32, v179
	v_lshrrev_b32_e32 v242, 3, v242
	v_lshl_add_u32 v242, v242, 1, v242
	v_mov_b32_e32 v243, 0
	v_lshl_add_u64 v[216:217], v[18:19], 0, v[242:243]
	s_nop 1
	v_permlane32_swap_b32_e32 v212, v213
	v_permlane32_swap_b32_e32 v214, v215
	global_store_dwordx4 v[216:217], v[212:215], off
	s_waitcnt vmcnt(2)
; DI float bf2f(unsigned b) { return __uint_as_float(b << 16); }
; template <int DQK, int W1, int DV, int VW, int MODE> ...
;     ...
; #pragma unroll
;   for (int cb = 0; cb < NCB; ++cb)
; #pragma unroll
;     for (int g = 0; g < 4; ++g) {
;       const int dv = 32 * cb + 8 * g + 4 * hi;
;       const u32x2 gg = ggv[cb * 4 + g];
;       float gv[4] = {bf2f(gg[0] & 0xffffu), bf2f(gg[0] >> 16), bf2f(gg[1] & 0xffffu), bf2f(gg[1] >> 16)};
;       float ov[4];
; #pragma unroll
;       for (int j = 0; j < 4; ++j) {
;         const float sg = gv[j] * __builtin_amdgcn_rcpf(1.f + __builtin_amdgcn_exp2f(-LOG2E * gv[j]));
;         ov[j] = o[cb][4 * g + j] * inv * sg;
;       }
;       *(unsigned*)((unsigned char*)yrow + dv) = pk4_fp8(ov[0] * Y_SCALE, ov[1] * Y_SCALE, ov[2] * Y_SCALE, ov[3] * Y_SCALE);
;       __builtin_amdgcn_sched_barrier(0);
;     }
	v_permlane32_swap_b32_e32 v38, v40
	v_permlane32_swap_b32_e32 v39, v41
	v_lshlrev_b32_e32 v20, 16, v40
	v_mul_f32_e32 v24, 0xbfb8aa3b, v20
	v_exp_f32_e32 v24, v24
	v_and_b32_e32 v21, 0xffff0000, v40
	v_mul_f32_e32 v2, v2, v0
	v_lshlrev_b32_e32 v22, 16, v41
	v_add_f32_e32 v24, 1.0, v24
	v_rcp_f32_e32 v24, v24
	v_mul_f32_e32 v3, v3, v0
	v_and_b32_e32 v23, 0xffff0000, v41
	v_mul_f32_e32 v4, v4, v0
	v_mul_f32_e32 v20, v24, v20
	v_mul_f32_e32 v2, v2, v20
	v_mul_f32_e32 v20, 0xbfb8aa3b, v21
	v_exp_f32_e32 v20, v20
	v_mul_f32_e32 v5, v5, v0
	v_med3_f32 v2, v2, s93, v223
	v_add_f32_e32 v20, 1.0, v20
	v_rcp_f32_e32 v20, v20
	s_nop 0
	v_mul_f32_e32 v20, v20, v21
	v_mul_f32_e32 v3, v3, v20
	v_mul_f32_e32 v20, 0xbfb8aa3b, v22
	v_exp_f32_e32 v20, v20
	s_nop 0
	v_med3_f32 v3, v3, s93, v223
	v_add_f32_e32 v20, 1.0, v20
	v_rcp_f32_e32 v20, v20
	s_nop 0
	v_mul_f32_e32 v20, v20, v22
	v_mul_f32_e32 v4, v4, v20
	v_mul_f32_e32 v20, 0xbfb8aa3b, v23
	v_exp_f32_e32 v20, v20
	s_nop 0
	v_add_f32_e32 v20, 1.0, v20
	v_rcp_f32_e32 v20, v20
	s_nop 0
	v_mul_f32_e32 v20, v20, v23
	v_mul_f32_e32 v5, v5, v20
	v_mov_b32_e32 v212, v1
	v_cvt_pk_fp8_f32 v212, v2, v3
	v_med3_f32 v2, v4, s93, v223
	v_med3_f32 v3, v5, s93, v223
	v_cvt_pk_fp8_f32 v212, v2, v3 op_sel:[0,0,1]
	s_waitcnt vmcnt(2)
	v_lshlrev_b32_e32 v2, 16, v38
	v_mul_f32_e32 v20, 0xbfb8aa3b, v2
	v_exp_f32_e32 v20, v20
	v_and_b32_e32 v3, 0xffff0000, v38
	v_mul_f32_e32 v6, v6, v0
	v_lshlrev_b32_e32 v4, 16, v39
	v_add_f32_e32 v20, 1.0, v20
	v_rcp_f32_e32 v20, v20
	v_and_b32_e32 v5, 0xffff0000, v39
	v_mul_f32_e32 v2, v20, v2
	v_mul_f32_e32 v2, v6, v2
	v_mul_f32_e32 v6, 0xbfb8aa3b, v3
	v_exp_f32_e32 v6, v6
	s_nop 0
	v_med3_f32 v2, v2, s93, v223
	v_add_f32_e32 v6, 1.0, v6
	v_rcp_f32_e32 v6, v6
	s_nop 0
	v_mul_f32_e32 v3, v6, v3
	v_mul_f32_e32 v6, v7, v0
	v_mul_f32_e32 v3, v6, v3
	v_mul_f32_e32 v6, 0xbfb8aa3b, v4
	v_exp_f32_e32 v6, v6
	s_nop 0
	v_med3_f32 v3, v3, s93, v223
	v_add_f32_e32 v6, 1.0, v6
	v_rcp_f32_e32 v6, v6
	s_nop 0
	v_mul_f32_e32 v4, v6, v4
	v_mul_f32_e32 v6, v8, v0
	v_mul_f32_e32 v4, v6, v4
	v_mul_f32_e32 v6, 0xbfb8aa3b, v5
	v_exp_f32_e32 v6, v6
	s_nop 0
	v_add_f32_e32 v6, 1.0, v6
	v_rcp_f32_e32 v6, v6
	s_nop 0
	v_mul_f32_e32 v5, v6, v5
	v_mul_f32_e32 v6, v9, v0
	v_mul_f32_e32 v5, v6, v5
	v_mov_b32_e32 v214, v1
	v_cvt_pk_fp8_f32 v214, v2, v3
	v_med3_f32 v2, v4, s93, v223
	v_med3_f32 v3, v5, s93, v223
	v_cvt_pk_fp8_f32 v214, v2, v3 op_sel:[0,0,1]
	s_waitcnt vmcnt(1)
	v_permlane32_swap_b32_e32 v34, v36
	v_permlane32_swap_b32_e32 v35, v37
	v_lshlrev_b32_e32 v2, 16, v36
	v_mul_f32_e32 v6, 0xbfb8aa3b, v2
	v_exp_f32_e32 v6, v6
	v_and_b32_e32 v3, 0xffff0000, v36
	v_lshlrev_b32_e32 v4, 16, v37
	v_and_b32_e32 v5, 0xffff0000, v37
	v_add_f32_e32 v6, 1.0, v6
	v_rcp_f32_e32 v6, v6
	s_nop 0
	v_mul_f32_e32 v2, v6, v2
	v_mul_f32_e32 v6, v10, v0
	v_mul_f32_e32 v2, v6, v2
	v_mul_f32_e32 v6, 0xbfb8aa3b, v3
	v_exp_f32_e32 v6, v6
	s_nop 0
	v_med3_f32 v2, v2, s93, v223
	v_add_f32_e32 v6, 1.0, v6
	v_rcp_f32_e32 v6, v6
	s_nop 0
	v_mul_f32_e32 v3, v6, v3
	v_mul_f32_e32 v6, v11, v0
	v_mul_f32_e32 v3, v6, v3
	v_mul_f32_e32 v6, 0xbfb8aa3b, v4
	v_exp_f32_e32 v6, v6
	s_nop 0
	v_med3_f32 v3, v3, s93, v223
	v_add_f32_e32 v6, 1.0, v6
	v_rcp_f32_e32 v6, v6
	s_nop 0
	v_mul_f32_e32 v4, v6, v4
	v_mul_f32_e32 v6, v12, v0
	v_mul_f32_e32 v4, v6, v4
	v_mul_f32_e32 v6, 0xbfb8aa3b, v5
	v_exp_f32_e32 v6, v6
	s_nop 0
	v_add_f32_e32 v6, 1.0, v6
	v_rcp_f32_e32 v6, v6
	s_nop 0
	v_mul_f32_e32 v5, v6, v5
	v_mul_f32_e32 v6, v13, v0
	v_mul_f32_e32 v5, v6, v5
	v_mov_b32_e32 v213, v1
	v_cvt_pk_fp8_f32 v213, v2, v3
	v_med3_f32 v2, v4, s93, v223
	v_med3_f32 v3, v5, s93, v223
	v_cvt_pk_fp8_f32 v213, v2, v3 op_sel:[0,0,1]
	s_waitcnt vmcnt(1)
	v_lshlrev_b32_e32 v2, 16, v34
	v_mul_f32_e32 v6, 0xbfb8aa3b, v2
	v_exp_f32_e32 v6, v6
	v_and_b32_e32 v3, 0xffff0000, v34
	v_lshlrev_b32_e32 v4, 16, v35
	v_and_b32_e32 v5, 0xffff0000, v35
	v_add_f32_e32 v6, 1.0, v6
	v_rcp_f32_e32 v6, v6
	s_nop 0
	v_mul_f32_e32 v2, v6, v2
	v_mul_f32_e32 v6, v14, v0
	v_mul_f32_e32 v2, v6, v2
	v_mul_f32_e32 v6, 0xbfb8aa3b, v3
	v_exp_f32_e32 v6, v6
	s_nop 0
	v_med3_f32 v2, v2, s93, v223
	v_add_f32_e32 v6, 1.0, v6
	v_rcp_f32_e32 v6, v6
	s_nop 0
	v_mul_f32_e32 v3, v6, v3
	v_mul_f32_e32 v6, v15, v0
	v_mul_f32_e32 v3, v6, v3
	v_mul_f32_e32 v6, 0xbfb8aa3b, v4
	v_exp_f32_e32 v6, v6
	s_nop 0
	v_med3_f32 v3, v3, s93, v223
	v_add_f32_e32 v6, 1.0, v6
	v_rcp_f32_e32 v6, v6
	s_nop 0
	v_mul_f32_e32 v4, v6, v4
	v_mul_f32_e32 v6, v16, v0
	v_mul_f32_e32 v4, v6, v4
	v_mul_f32_e32 v6, 0xbfb8aa3b, v5
	v_exp_f32_e32 v6, v6
	v_mul_f32_e32 v0, v17, v0
	v_add_f32_e32 v6, 1.0, v6
	v_rcp_f32_e32 v6, v6
	s_nop 0
	v_mul_f32_e32 v5, v6, v5
	v_mul_f32_e32 v0, v0, v5
	v_mov_b32_e32 v215, v1
	v_cvt_pk_fp8_f32 v215, v2, v3
	v_med3_f32 v2, v4, s93, v223
	v_med3_f32 v0, v0, s93, v223
	v_cvt_pk_fp8_f32 v215, v2, v0 op_sel:[0,0,1]
	s_nop 1
	v_permlane32_swap_b32_e32 v212, v213
	v_permlane32_swap_b32_e32 v214, v215
	global_store_dwordx4 v[216:217], v[212:215], off offset:32
	s_movk_i32 s20, 0x600
	s_mov_b32 s86, 0x800000
	s_movk_i32 s87, 0x3fff
	v_readlane_b32 s3, v254, 29
